# counted waits to first consumer in the residual epilogues: vmcnt(15) in front of each residual load's first use (load k is used after k stores) instead of one vmcnt(0) for all 16; on top of v21
# baseline (speedup 1.0000x reference)
.LBB0_773:
	v_lshl_or_b32 v130, s17, 8, v239
	v_lshl_add_u32 v216, s20, 8, v223
	v_ashrrev_i32_e32 v131, 31, v130
	v_lshlrev_b64 v[220:221], 1, v[130:131]
	v_ashrrev_i32_e32 v217, 31, v216
	v_lshl_add_u64 v[130:131], s[86:87], 0, v[220:221]
	v_lshlrev_b64 v[248:249], 12, v[216:217]
	v_lshl_add_u64 v[132:133], v[130:131], 0, v[248:249]
	global_load_dwordx4 v[190:193], v[132:133], off
	global_load_dwordx4 v[186:189], v[132:133], off offset:256
	v_or_b32_e32 v132, 16, v216
	v_ashrrev_i32_e32 v133, 31, v132
	v_lshlrev_b64 v[246:247], 12, v[132:133]
	v_lshl_add_u64 v[132:133], v[130:131], 0, v[246:247]
	global_load_dwordx4 v[182:185], v[132:133], off
	global_load_dwordx4 v[178:181], v[132:133], off offset:256
	v_or_b32_e32 v132, 32, v216
	v_ashrrev_i32_e32 v133, 31, v132
	v_lshlrev_b64 v[244:245], 12, v[132:133]
	v_lshl_add_u64 v[132:133], v[130:131], 0, v[244:245]
	global_load_dwordx4 v[174:177], v[132:133], off
	global_load_dwordx4 v[170:173], v[132:133], off offset:256
	v_or_b32_e32 v132, 48, v216
	v_ashrrev_i32_e32 v133, 31, v132
	v_lshlrev_b64 v[240:241], 12, v[132:133]
	v_lshl_add_u64 v[132:133], v[130:131], 0, v[240:241]
	global_load_dwordx4 v[166:169], v[132:133], off
	global_load_dwordx4 v[162:165], v[132:133], off offset:256
	s_mov_b64 s[20:21], 0x80000
	v_lshl_add_u64 v[236:237], v[248:249], 0, s[20:21]
	s_mov_b64 s[20:21], 0x90000
	v_lshl_add_u64 v[232:233], v[248:249], 0, s[20:21]
	s_mov_b64 s[20:21], 0xa0000
	v_lshl_add_u64 v[132:133], v[130:131], 0, v[236:237]
	v_lshl_add_u64 v[228:229], v[248:249], 0, s[20:21]
	s_mov_b64 s[20:21], 0xb0000
	global_load_dwordx4 v[158:161], v[132:133], off
	global_load_dwordx4 v[154:157], v[132:133], off offset:256
	v_lshl_add_u64 v[132:133], v[130:131], 0, v[232:233]
	v_lshl_add_u64 v[226:227], v[248:249], 0, s[20:21]
	v_lshl_add_u64 v[248:249], s[86:87], 0, v[248:249]
	global_load_dwordx4 v[150:153], v[132:133], off
	global_load_dwordx4 v[146:149], v[132:133], off offset:256
	v_lshl_add_u64 v[132:133], v[130:131], 0, v[228:229]
	v_lshl_add_u64 v[130:131], v[130:131], 0, v[226:227]
	v_lshl_add_u64 v[248:249], v[248:249], 0, v[220:221]
	global_load_dwordx4 v[142:145], v[132:133], off
	global_load_dwordx4 v[138:141], v[132:133], off offset:256
	global_load_dwordx4 v[134:137], v[130:131], off
	s_nop 0
	global_load_dwordx4 v[130:133], v[130:131], off offset:256
	s_movk_i32 s17, 0x80
	s_waitcnt vmcnt(15)
	v_lshlrev_b32_e32 v200, 16, v190
	v_and_b32_e32 v201, 0xffff0000, v190
	v_lshlrev_b32_e32 v190, 16, v191
	v_and_b32_e32 v191, 0xffff0000, v191
	v_pk_fma_f32 v[126:127], v[126:127], v[242:243], v[200:201] op_sel_hi:[1,0,1]
	v_pk_fma_f32 v[128:129], v[128:129], v[242:243], v[190:191] op_sel_hi:[1,0,1]
	v_cvt_pk_bf16_f32 v126, v126, v127
	v_cvt_pk_bf16_f32 v127, v128, v129
	v_lshlrev_b32_e32 v128, 16, v192
	v_and_b32_e32 v129, 0xffff0000, v192
	v_pk_fma_f32 v[122:123], v[122:123], v[242:243], v[128:129] op_sel_hi:[1,0,1]
	s_nop 0
	v_cvt_pk_bf16_f32 v128, v122, v123
	v_lshlrev_b32_e32 v122, 16, v193
	v_and_b32_e32 v123, 0xffff0000, v193
	v_pk_fma_f32 v[122:123], v[124:125], v[242:243], v[122:123] op_sel_hi:[1,0,1]
	v_and_b32_e32 v125, 0xffff0000, v127
	v_cvt_pk_bf16_f32 v129, v122, v123
	v_and_b32_e32 v123, 0xffff0000, v126
	v_lshlrev_b32_e32 v122, 16, v126
	v_mul_f32_e32 v123, v123, v123
	v_lshlrev_b32_e32 v124, 16, v127
	v_fmac_f32_e32 v123, v122, v122
	v_mul_f32_e32 v122, v125, v125
	global_store_dwordx4 v[248:249], v[126:129], off
	v_fmac_f32_e32 v122, v124, v124
	v_add_f32_e32 v122, v123, v122
	v_lshlrev_b32_e32 v126, 16, v128
	v_and_b32_e32 v127, 0xffff0000, v128
	v_lshlrev_b32_e32 v128, 16, v129
	v_and_b32_e32 v129, 0xffff0000, v129
	v_mul_f32_e32 v123, v127, v127
	v_mul_f32_e32 v124, v129, v129
	v_fmac_f32_e32 v123, v126, v126
	v_fmac_f32_e32 v124, v128, v128
	v_add_f32_e32 v123, v123, v124
	v_add_f32_e32 v124, v122, v123
	s_waitcnt vmcnt(15)
	v_lshlrev_b32_e32 v122, 16, v186
	v_and_b32_e32 v123, 0xffff0000, v186
	v_pk_fma_f32 v[118:119], v[118:119], v[242:243], v[122:123] op_sel_hi:[1,0,1]
	v_lshlrev_b32_e32 v122, 16, v187
	v_and_b32_e32 v123, 0xffff0000, v187
	v_pk_fma_f32 v[120:121], v[120:121], v[242:243], v[122:123] op_sel_hi:[1,0,1]
	v_cvt_pk_bf16_f32 v118, v118, v119
	v_cvt_pk_bf16_f32 v119, v120, v121
	v_lshlrev_b32_e32 v120, 16, v188
	v_and_b32_e32 v121, 0xffff0000, v188
	v_pk_fma_f32 v[114:115], v[114:115], v[242:243], v[120:121] op_sel_hi:[1,0,1]
	s_nop 0
	v_cvt_pk_bf16_f32 v120, v114, v115
	v_lshlrev_b32_e32 v114, 16, v189
	v_and_b32_e32 v115, 0xffff0000, v189
	v_pk_fma_f32 v[114:115], v[116:117], v[242:243], v[114:115] op_sel_hi:[1,0,1]
	v_and_b32_e32 v117, 0xffff0000, v119
	v_cvt_pk_bf16_f32 v121, v114, v115
	v_and_b32_e32 v115, 0xffff0000, v118
	v_lshlrev_b32_e32 v114, 16, v118
	v_mul_f32_e32 v115, v115, v115
	v_lshlrev_b32_e32 v116, 16, v119
	v_fmac_f32_e32 v115, v114, v114
	v_mul_f32_e32 v114, v117, v117
	global_store_dwordx4 v[248:249], v[118:121], off offset:256
	v_fmac_f32_e32 v114, v116, v116
	v_add_f32_e32 v114, v115, v114
	v_and_b32_e32 v119, 0xffff0000, v120
	v_lshlrev_b32_e32 v118, 16, v120
	v_mul_f32_e32 v115, v119, v119
	v_fmac_f32_e32 v115, v118, v118
	s_waitcnt vmcnt(15)
	v_lshlrev_b32_e32 v118, 16, v182
	v_and_b32_e32 v119, 0xffff0000, v182
	v_pk_fma_f32 v[110:111], v[110:111], v[238:239], v[118:119] op_sel_hi:[1,0,1]
	v_lshlrev_b32_e32 v118, 16, v183
	v_and_b32_e32 v119, 0xffff0000, v183
	v_pk_fma_f32 v[112:113], v[112:113], v[238:239], v[118:119] op_sel_hi:[1,0,1]
	v_cvt_pk_bf16_f32 v110, v110, v111
	v_cvt_pk_bf16_f32 v111, v112, v113
	v_lshlrev_b32_e32 v112, 16, v184
	v_and_b32_e32 v113, 0xffff0000, v184
	v_pk_fma_f32 v[106:107], v[106:107], v[238:239], v[112:113] op_sel_hi:[1,0,1]
	v_lshlrev_b32_e32 v120, 16, v121
	v_and_b32_e32 v121, 0xffff0000, v121
	v_cvt_pk_bf16_f32 v112, v106, v107
	v_lshlrev_b32_e32 v106, 16, v185
	v_and_b32_e32 v107, 0xffff0000, v185
	v_mul_f32_e32 v116, v121, v121
	v_pk_fma_f32 v[106:107], v[108:109], v[238:239], v[106:107] op_sel_hi:[1,0,1]
	v_fmac_f32_e32 v116, v120, v120
	v_cvt_pk_bf16_f32 v113, v106, v107
	v_and_b32_e32 v107, 0xffff0000, v110
	v_add_f32_e32 v115, v115, v116
	v_lshl_add_u64 v[116:117], s[86:87], 0, v[246:247]
	v_lshlrev_b32_e32 v106, 16, v110
	v_and_b32_e32 v109, 0xffff0000, v111
	v_mul_f32_e32 v107, v107, v107
	v_lshl_add_u64 v[116:117], v[116:117], 0, v[220:221]
	v_lshlrev_b32_e32 v108, 16, v111
	v_fmac_f32_e32 v107, v106, v106
	v_mul_f32_e32 v106, v109, v109
	global_store_dwordx4 v[116:117], v[110:113], off
	v_fmac_f32_e32 v106, v108, v108
	v_add_f32_e32 v106, v107, v106
	v_lshlrev_b32_e32 v110, 16, v112
	v_and_b32_e32 v111, 0xffff0000, v112
	v_lshlrev_b32_e32 v112, 16, v113
	v_and_b32_e32 v113, 0xffff0000, v113
	v_mul_f32_e32 v107, v111, v111
	v_mul_f32_e32 v108, v113, v113
	v_fmac_f32_e32 v107, v110, v110
	v_fmac_f32_e32 v108, v112, v112
	v_add_f32_e32 v107, v107, v108
	v_add_f32_e32 v108, v106, v107
	s_waitcnt vmcnt(15)
	v_lshlrev_b32_e32 v106, 16, v178
	v_and_b32_e32 v107, 0xffff0000, v178
	v_pk_fma_f32 v[102:103], v[102:103], v[238:239], v[106:107] op_sel_hi:[1,0,1]
	v_lshlrev_b32_e32 v106, 16, v179
	v_and_b32_e32 v107, 0xffff0000, v179
	v_pk_fma_f32 v[104:105], v[104:105], v[238:239], v[106:107] op_sel_hi:[1,0,1]
	v_cvt_pk_bf16_f32 v102, v102, v103
	v_cvt_pk_bf16_f32 v103, v104, v105
	v_lshlrev_b32_e32 v104, 16, v180
	v_and_b32_e32 v105, 0xffff0000, v180
	v_pk_fma_f32 v[98:99], v[98:99], v[238:239], v[104:105] op_sel_hi:[1,0,1]
	v_add_f32_e32 v114, v114, v115
	v_cvt_pk_bf16_f32 v104, v98, v99
	v_lshlrev_b32_e32 v98, 16, v181
	v_and_b32_e32 v99, 0xffff0000, v181
	v_pk_fma_f32 v[98:99], v[100:101], v[238:239], v[98:99] op_sel_hi:[1,0,1]
	v_and_b32_e32 v101, 0xffff0000, v103
	v_cvt_pk_bf16_f32 v105, v98, v99
	v_and_b32_e32 v99, 0xffff0000, v102
	v_lshlrev_b32_e32 v98, 16, v102
	v_mul_f32_e32 v99, v99, v99
	v_lshlrev_b32_e32 v100, 16, v103
	v_fmac_f32_e32 v99, v98, v98
	v_mul_f32_e32 v98, v101, v101
	global_store_dwordx4 v[116:117], v[102:105], off offset:256
	v_fmac_f32_e32 v98, v100, v100
	v_add_f32_e32 v98, v99, v98
	v_and_b32_e32 v103, 0xffff0000, v104
	v_lshlrev_b32_e32 v102, 16, v104
	v_mul_f32_e32 v99, v103, v103
	v_fmac_f32_e32 v99, v102, v102
	s_waitcnt vmcnt(15)
	v_lshlrev_b32_e32 v102, 16, v174
	v_and_b32_e32 v103, 0xffff0000, v174
	v_pk_fma_f32 v[94:95], v[94:95], v[234:235], v[102:103] op_sel_hi:[1,0,1]
	v_lshlrev_b32_e32 v102, 16, v175
	v_and_b32_e32 v103, 0xffff0000, v175
	v_pk_fma_f32 v[96:97], v[96:97], v[234:235], v[102:103] op_sel_hi:[1,0,1]
	v_cvt_pk_bf16_f32 v94, v94, v95
	v_cvt_pk_bf16_f32 v95, v96, v97
	v_lshlrev_b32_e32 v96, 16, v176
	v_and_b32_e32 v97, 0xffff0000, v176
	v_pk_fma_f32 v[90:91], v[90:91], v[234:235], v[96:97] op_sel_hi:[1,0,1]
	v_lshlrev_b32_e32 v104, 16, v105
	v_and_b32_e32 v105, 0xffff0000, v105
	v_cvt_pk_bf16_f32 v96, v90, v91
	v_lshlrev_b32_e32 v90, 16, v177
	v_and_b32_e32 v91, 0xffff0000, v177
	v_mul_f32_e32 v100, v105, v105
	v_pk_fma_f32 v[90:91], v[92:93], v[234:235], v[90:91] op_sel_hi:[1,0,1]
	v_fmac_f32_e32 v100, v104, v104
	v_cvt_pk_bf16_f32 v97, v90, v91
	v_and_b32_e32 v91, 0xffff0000, v94
	v_add_f32_e32 v99, v99, v100
	v_lshl_add_u64 v[100:101], s[86:87], 0, v[244:245]
	v_lshlrev_b32_e32 v90, 16, v94
	v_and_b32_e32 v93, 0xffff0000, v95
	v_mul_f32_e32 v91, v91, v91
	v_lshl_add_u64 v[100:101], v[100:101], 0, v[220:221]
	v_lshlrev_b32_e32 v92, 16, v95
	v_fmac_f32_e32 v91, v90, v90
	v_mul_f32_e32 v90, v93, v93
	global_store_dwordx4 v[100:101], v[94:97], off
	v_fmac_f32_e32 v90, v92, v92
	v_add_f32_e32 v90, v91, v90
	v_lshlrev_b32_e32 v94, 16, v96
	v_and_b32_e32 v95, 0xffff0000, v96
	v_lshlrev_b32_e32 v96, 16, v97
	v_and_b32_e32 v97, 0xffff0000, v97
	v_mul_f32_e32 v91, v95, v95
	v_mul_f32_e32 v92, v97, v97
	v_fmac_f32_e32 v91, v94, v94
	v_fmac_f32_e32 v92, v96, v96
	v_add_f32_e32 v91, v91, v92
	v_add_f32_e32 v92, v90, v91
	s_waitcnt vmcnt(15)
	v_lshlrev_b32_e32 v90, 16, v170
	v_and_b32_e32 v91, 0xffff0000, v170
	v_pk_fma_f32 v[86:87], v[86:87], v[234:235], v[90:91] op_sel_hi:[1,0,1]
	v_lshlrev_b32_e32 v90, 16, v171
	v_and_b32_e32 v91, 0xffff0000, v171
	v_pk_fma_f32 v[88:89], v[88:89], v[234:235], v[90:91] op_sel_hi:[1,0,1]
	v_cvt_pk_bf16_f32 v86, v86, v87
	v_cvt_pk_bf16_f32 v87, v88, v89
	v_lshlrev_b32_e32 v88, 16, v172
	v_and_b32_e32 v89, 0xffff0000, v172
	v_pk_fma_f32 v[82:83], v[82:83], v[234:235], v[88:89] op_sel_hi:[1,0,1]
	v_add_f32_e32 v98, v98, v99
	v_cvt_pk_bf16_f32 v88, v82, v83
	v_lshlrev_b32_e32 v82, 16, v173
	v_and_b32_e32 v83, 0xffff0000, v173
	v_pk_fma_f32 v[82:83], v[84:85], v[234:235], v[82:83] op_sel_hi:[1,0,1]
	v_and_b32_e32 v85, 0xffff0000, v87
	v_cvt_pk_bf16_f32 v89, v82, v83
	v_and_b32_e32 v83, 0xffff0000, v86
	v_lshlrev_b32_e32 v82, 16, v86
	v_mul_f32_e32 v83, v83, v83
	v_lshlrev_b32_e32 v84, 16, v87
	v_fmac_f32_e32 v83, v82, v82
	v_mul_f32_e32 v82, v85, v85
	global_store_dwordx4 v[100:101], v[86:89], off offset:256
	v_fmac_f32_e32 v82, v84, v84
	v_add_f32_e32 v82, v83, v82
	v_and_b32_e32 v87, 0xffff0000, v88
	v_lshlrev_b32_e32 v86, 16, v88
	v_mul_f32_e32 v83, v87, v87
	v_fmac_f32_e32 v83, v86, v86
	s_waitcnt vmcnt(15)
	v_lshlrev_b32_e32 v86, 16, v166
	v_and_b32_e32 v87, 0xffff0000, v166
	v_pk_fma_f32 v[78:79], v[78:79], v[230:231], v[86:87] op_sel_hi:[1,0,1]
	v_lshlrev_b32_e32 v86, 16, v167
	v_and_b32_e32 v87, 0xffff0000, v167
	v_pk_fma_f32 v[80:81], v[80:81], v[230:231], v[86:87] op_sel_hi:[1,0,1]
	v_cvt_pk_bf16_f32 v78, v78, v79
	v_cvt_pk_bf16_f32 v79, v80, v81
	v_lshlrev_b32_e32 v80, 16, v168
	v_and_b32_e32 v81, 0xffff0000, v168
	v_pk_fma_f32 v[74:75], v[74:75], v[230:231], v[80:81] op_sel_hi:[1,0,1]
	v_lshlrev_b32_e32 v88, 16, v89
	v_and_b32_e32 v89, 0xffff0000, v89
	v_cvt_pk_bf16_f32 v80, v74, v75
	v_lshlrev_b32_e32 v74, 16, v169
	v_and_b32_e32 v75, 0xffff0000, v169
	v_mul_f32_e32 v84, v89, v89
	v_pk_fma_f32 v[74:75], v[76:77], v[230:231], v[74:75] op_sel_hi:[1,0,1]
	v_fmac_f32_e32 v84, v88, v88
	v_cvt_pk_bf16_f32 v81, v74, v75
	v_and_b32_e32 v75, 0xffff0000, v78
	v_add_f32_e32 v83, v83, v84
	v_lshl_add_u64 v[84:85], s[86:87], 0, v[240:241]
	v_lshlrev_b32_e32 v74, 16, v78
	v_and_b32_e32 v77, 0xffff0000, v79
	v_mul_f32_e32 v75, v75, v75
	v_lshl_add_u64 v[84:85], v[84:85], 0, v[220:221]
	v_lshlrev_b32_e32 v76, 16, v79
	v_fmac_f32_e32 v75, v74, v74
	v_mul_f32_e32 v74, v77, v77
	global_store_dwordx4 v[84:85], v[78:81], off
	v_fmac_f32_e32 v74, v76, v76
	v_add_f32_e32 v74, v75, v74
	v_lshlrev_b32_e32 v78, 16, v80
	v_and_b32_e32 v79, 0xffff0000, v80
	v_lshlrev_b32_e32 v80, 16, v81
	v_and_b32_e32 v81, 0xffff0000, v81
	v_mul_f32_e32 v75, v79, v79
	v_mul_f32_e32 v76, v81, v81
	v_fmac_f32_e32 v75, v78, v78
	v_fmac_f32_e32 v76, v80, v80
	v_add_f32_e32 v75, v75, v76
	v_add_f32_e32 v76, v74, v75
	s_waitcnt vmcnt(15)
	v_lshlrev_b32_e32 v74, 16, v162
	v_and_b32_e32 v75, 0xffff0000, v162
	v_pk_fma_f32 v[70:71], v[70:71], v[230:231], v[74:75] op_sel_hi:[1,0,1]
	v_lshlrev_b32_e32 v74, 16, v163
	v_and_b32_e32 v75, 0xffff0000, v163
	v_pk_fma_f32 v[72:73], v[72:73], v[230:231], v[74:75] op_sel_hi:[1,0,1]
	v_cvt_pk_bf16_f32 v70, v70, v71
	v_cvt_pk_bf16_f32 v71, v72, v73
	v_lshlrev_b32_e32 v72, 16, v164
	v_and_b32_e32 v73, 0xffff0000, v164
	v_pk_fma_f32 v[66:67], v[66:67], v[230:231], v[72:73] op_sel_hi:[1,0,1]
	v_add_f32_e32 v82, v82, v83
	v_cvt_pk_bf16_f32 v72, v66, v67
	v_lshlrev_b32_e32 v66, 16, v165
	v_and_b32_e32 v67, 0xffff0000, v165
	v_pk_fma_f32 v[66:67], v[68:69], v[230:231], v[66:67] op_sel_hi:[1,0,1]
	v_and_b32_e32 v69, 0xffff0000, v71
	v_cvt_pk_bf16_f32 v73, v66, v67
	v_and_b32_e32 v67, 0xffff0000, v70
	v_lshlrev_b32_e32 v66, 16, v70
	v_mul_f32_e32 v67, v67, v67
	v_lshlrev_b32_e32 v68, 16, v71
	v_fmac_f32_e32 v67, v66, v66
	v_mul_f32_e32 v66, v69, v69
	global_store_dwordx4 v[84:85], v[70:73], off offset:256
	v_fmac_f32_e32 v66, v68, v68
	v_add_f32_e32 v66, v67, v66
	v_lshlrev_b32_e32 v70, 16, v72
	v_and_b32_e32 v71, 0xffff0000, v72
	v_lshlrev_b32_e32 v72, 16, v73
	v_and_b32_e32 v73, 0xffff0000, v73
	v_mul_f32_e32 v67, v71, v71
	v_mul_f32_e32 v68, v73, v73
	v_fmac_f32_e32 v67, v70, v70
	v_fmac_f32_e32 v68, v72, v72
	v_add_f32_e32 v67, v67, v68
	s_waitcnt vmcnt(15)
	v_lshlrev_b32_e32 v68, 16, v158
	v_and_b32_e32 v69, 0xffff0000, v158
	v_pk_fma_f32 v[62:63], v[62:63], v[224:225], v[68:69] op_sel_hi:[1,0,1]
	v_lshlrev_b32_e32 v68, 16, v159
	v_and_b32_e32 v69, 0xffff0000, v159
	v_pk_fma_f32 v[64:65], v[64:65], v[224:225], v[68:69] op_sel_hi:[1,0,1]
	v_cvt_pk_bf16_f32 v62, v62, v63
	v_cvt_pk_bf16_f32 v63, v64, v65
	v_lshlrev_b32_e32 v64, 16, v160
	v_and_b32_e32 v65, 0xffff0000, v160
	v_pk_fma_f32 v[58:59], v[58:59], v[224:225], v[64:65] op_sel_hi:[1,0,1]
	v_add_f32_e32 v66, v66, v67
	v_cvt_pk_bf16_f32 v64, v58, v59
	v_lshlrev_b32_e32 v58, 16, v161
	v_and_b32_e32 v59, 0xffff0000, v161
	v_pk_fma_f32 v[58:59], v[60:61], v[224:225], v[58:59] op_sel_hi:[1,0,1]
	v_add_f32_e32 v70, v76, v66
	v_cvt_pk_bf16_f32 v65, v58, v59
	v_and_b32_e32 v59, 0xffff0000, v62
	v_lshl_add_u64 v[66:67], s[86:87], 0, v[236:237]
	v_lshlrev_b32_e32 v58, 16, v62
	v_and_b32_e32 v61, 0xffff0000, v63
	v_mul_f32_e32 v59, v59, v59
	v_lshl_add_u64 v[66:67], v[66:67], 0, v[220:221]
	v_lshlrev_b32_e32 v60, 16, v63
	v_fmac_f32_e32 v59, v58, v58
	v_mul_f32_e32 v58, v61, v61
	global_store_dwordx4 v[66:67], v[62:65], off
	v_fmac_f32_e32 v58, v60, v60
	v_add_f32_e32 v58, v59, v58
	v_lshlrev_b32_e32 v62, 16, v64
	v_and_b32_e32 v63, 0xffff0000, v64
	v_lshlrev_b32_e32 v64, 16, v65
	v_and_b32_e32 v65, 0xffff0000, v65
	v_mul_f32_e32 v59, v63, v63
	v_mul_f32_e32 v60, v65, v65
	v_fmac_f32_e32 v59, v62, v62
	v_fmac_f32_e32 v60, v64, v64
	v_add_f32_e32 v59, v59, v60
	v_add_f32_e32 v60, v58, v59
	s_waitcnt vmcnt(15)
	v_lshlrev_b32_e32 v58, 16, v154
	v_and_b32_e32 v59, 0xffff0000, v154
	v_pk_fma_f32 v[54:55], v[54:55], v[224:225], v[58:59] op_sel_hi:[1,0,1]
	v_lshlrev_b32_e32 v58, 16, v155
	v_and_b32_e32 v59, 0xffff0000, v155
	v_pk_fma_f32 v[56:57], v[56:57], v[224:225], v[58:59] op_sel_hi:[1,0,1]
	v_cvt_pk_bf16_f32 v54, v54, v55
	v_cvt_pk_bf16_f32 v55, v56, v57
	v_lshlrev_b32_e32 v56, 16, v156
	v_and_b32_e32 v57, 0xffff0000, v156
	v_pk_fma_f32 v[50:51], v[50:51], v[224:225], v[56:57] op_sel_hi:[1,0,1]
	v_add_f32_e32 v114, v124, v114
	v_cvt_pk_bf16_f32 v56, v50, v51
	v_lshlrev_b32_e32 v50, 16, v157
	v_and_b32_e32 v51, 0xffff0000, v157
	v_pk_fma_f32 v[50:51], v[52:53], v[224:225], v[50:51] op_sel_hi:[1,0,1]
	v_and_b32_e32 v53, 0xffff0000, v55
	v_cvt_pk_bf16_f32 v57, v50, v51
	v_and_b32_e32 v51, 0xffff0000, v54
	v_lshlrev_b32_e32 v50, 16, v54
	v_mul_f32_e32 v51, v51, v51
	v_lshlrev_b32_e32 v52, 16, v55
	v_fmac_f32_e32 v51, v50, v50
	v_mul_f32_e32 v50, v53, v53
	global_store_dwordx4 v[66:67], v[54:57], off offset:256
	v_fmac_f32_e32 v50, v52, v52
	v_add_f32_e32 v50, v51, v50
	v_lshlrev_b32_e32 v54, 16, v56
	v_and_b32_e32 v55, 0xffff0000, v56
	v_lshlrev_b32_e32 v56, 16, v57
	v_and_b32_e32 v57, 0xffff0000, v57
	v_mul_f32_e32 v51, v55, v55
	v_mul_f32_e32 v52, v57, v57
	v_fmac_f32_e32 v51, v54, v54
	v_fmac_f32_e32 v52, v56, v56
	v_add_f32_e32 v51, v51, v52
	s_waitcnt vmcnt(15)
	v_lshlrev_b32_e32 v52, 16, v150
	v_and_b32_e32 v53, 0xffff0000, v150
	v_pk_fma_f32 v[46:47], v[46:47], v[222:223], v[52:53] op_sel_hi:[1,0,1]
	v_lshlrev_b32_e32 v52, 16, v151
	v_and_b32_e32 v53, 0xffff0000, v151
	v_pk_fma_f32 v[48:49], v[48:49], v[222:223], v[52:53] op_sel_hi:[1,0,1]
	v_cvt_pk_bf16_f32 v46, v46, v47
	v_cvt_pk_bf16_f32 v47, v48, v49
	v_lshlrev_b32_e32 v48, 16, v152
	v_and_b32_e32 v49, 0xffff0000, v152
	v_pk_fma_f32 v[42:43], v[42:43], v[222:223], v[48:49] op_sel_hi:[1,0,1]
	v_add_f32_e32 v50, v50, v51
	v_cvt_pk_bf16_f32 v48, v42, v43
	v_lshlrev_b32_e32 v42, 16, v153
	v_and_b32_e32 v43, 0xffff0000, v153
	v_pk_fma_f32 v[42:43], v[44:45], v[222:223], v[42:43] op_sel_hi:[1,0,1]
	v_add_f32_e32 v54, v60, v50
	v_cvt_pk_bf16_f32 v49, v42, v43
	v_and_b32_e32 v43, 0xffff0000, v46
	v_lshl_add_u64 v[50:51], s[86:87], 0, v[232:233]
	v_lshlrev_b32_e32 v42, 16, v46
	v_and_b32_e32 v45, 0xffff0000, v47
	v_mul_f32_e32 v43, v43, v43
	v_lshl_add_u64 v[50:51], v[50:51], 0, v[220:221]
	v_lshlrev_b32_e32 v44, 16, v47
	v_fmac_f32_e32 v43, v42, v42
	v_mul_f32_e32 v42, v45, v45
	global_store_dwordx4 v[50:51], v[46:49], off
	v_fmac_f32_e32 v42, v44, v44
	v_add_f32_e32 v42, v43, v42
	v_lshlrev_b32_e32 v46, 16, v48
	v_and_b32_e32 v47, 0xffff0000, v48
	v_lshlrev_b32_e32 v48, 16, v49
	v_and_b32_e32 v49, 0xffff0000, v49
	v_mul_f32_e32 v43, v47, v47
	v_mul_f32_e32 v44, v49, v49
	v_fmac_f32_e32 v43, v46, v46
	v_fmac_f32_e32 v44, v48, v48
	v_add_f32_e32 v43, v43, v44
	v_add_f32_e32 v44, v42, v43
	s_waitcnt vmcnt(15)
	v_lshlrev_b32_e32 v42, 16, v146
	v_and_b32_e32 v43, 0xffff0000, v146
	v_pk_fma_f32 v[38:39], v[38:39], v[222:223], v[42:43] op_sel_hi:[1,0,1]
	v_lshlrev_b32_e32 v42, 16, v147
	v_and_b32_e32 v43, 0xffff0000, v147
	v_pk_fma_f32 v[40:41], v[40:41], v[222:223], v[42:43] op_sel_hi:[1,0,1]
	v_cvt_pk_bf16_f32 v38, v38, v39
	v_cvt_pk_bf16_f32 v39, v40, v41
	v_lshlrev_b32_e32 v40, 16, v148
	v_and_b32_e32 v41, 0xffff0000, v148
	v_pk_fma_f32 v[34:35], v[34:35], v[222:223], v[40:41] op_sel_hi:[1,0,1]
	v_add_f32_e32 v98, v108, v98
	v_cvt_pk_bf16_f32 v40, v34, v35
	v_lshlrev_b32_e32 v34, 16, v149
	v_and_b32_e32 v35, 0xffff0000, v149
	v_pk_fma_f32 v[34:35], v[36:37], v[222:223], v[34:35] op_sel_hi:[1,0,1]
	v_and_b32_e32 v37, 0xffff0000, v39
	v_cvt_pk_bf16_f32 v41, v34, v35
	v_and_b32_e32 v35, 0xffff0000, v38
	v_lshlrev_b32_e32 v34, 16, v38
	v_mul_f32_e32 v35, v35, v35
	v_lshlrev_b32_e32 v36, 16, v39
	v_fmac_f32_e32 v35, v34, v34
	v_mul_f32_e32 v34, v37, v37
	global_store_dwordx4 v[50:51], v[38:41], off offset:256
	v_fmac_f32_e32 v34, v36, v36
	v_add_f32_e32 v34, v35, v34
	v_lshlrev_b32_e32 v38, 16, v40
	v_and_b32_e32 v39, 0xffff0000, v40
	v_lshlrev_b32_e32 v40, 16, v41
	v_and_b32_e32 v41, 0xffff0000, v41
	v_mul_f32_e32 v35, v39, v39
	v_mul_f32_e32 v36, v41, v41
	v_fmac_f32_e32 v35, v38, v38
	v_fmac_f32_e32 v36, v40, v40
	v_add_f32_e32 v35, v35, v36
	s_waitcnt vmcnt(15)
	v_lshlrev_b32_e32 v36, 16, v142
	v_and_b32_e32 v37, 0xffff0000, v142
	v_pk_fma_f32 v[30:31], v[30:31], v[218:219], v[36:37] op_sel_hi:[1,0,1]
	v_lshlrev_b32_e32 v36, 16, v143
	v_and_b32_e32 v37, 0xffff0000, v143
	v_pk_fma_f32 v[32:33], v[32:33], v[218:219], v[36:37] op_sel_hi:[1,0,1]
	v_cvt_pk_bf16_f32 v30, v30, v31
	v_cvt_pk_bf16_f32 v31, v32, v33
	v_lshlrev_b32_e32 v32, 16, v144
	v_and_b32_e32 v33, 0xffff0000, v144
	v_pk_fma_f32 v[26:27], v[26:27], v[218:219], v[32:33] op_sel_hi:[1,0,1]
	v_add_f32_e32 v34, v34, v35
	v_cvt_pk_bf16_f32 v32, v26, v27
	v_lshlrev_b32_e32 v26, 16, v145
	v_and_b32_e32 v27, 0xffff0000, v145
	v_pk_fma_f32 v[26:27], v[28:29], v[218:219], v[26:27] op_sel_hi:[1,0,1]
	v_add_f32_e32 v38, v44, v34
	v_cvt_pk_bf16_f32 v33, v26, v27
	v_and_b32_e32 v27, 0xffff0000, v30
	v_lshl_add_u64 v[34:35], s[86:87], 0, v[228:229]
	v_lshlrev_b32_e32 v26, 16, v30
	v_and_b32_e32 v29, 0xffff0000, v31
	v_mul_f32_e32 v27, v27, v27
	v_lshl_add_u64 v[34:35], v[34:35], 0, v[220:221]
	v_lshlrev_b32_e32 v28, 16, v31
	v_fmac_f32_e32 v27, v26, v26
	v_mul_f32_e32 v26, v29, v29
	global_store_dwordx4 v[34:35], v[30:33], off
	v_fmac_f32_e32 v26, v28, v28
	v_add_f32_e32 v26, v27, v26
	v_lshlrev_b32_e32 v30, 16, v32
	v_and_b32_e32 v31, 0xffff0000, v32
	v_lshlrev_b32_e32 v32, 16, v33
	v_and_b32_e32 v33, 0xffff0000, v33
	v_mul_f32_e32 v27, v31, v31
	v_mul_f32_e32 v28, v33, v33
	v_fmac_f32_e32 v27, v30, v30
	v_fmac_f32_e32 v28, v32, v32
	v_add_f32_e32 v27, v27, v28
	v_add_f32_e32 v28, v26, v27
	s_waitcnt vmcnt(15)
	v_lshlrev_b32_e32 v26, 16, v138
	v_and_b32_e32 v27, 0xffff0000, v138
	v_pk_fma_f32 v[22:23], v[22:23], v[218:219], v[26:27] op_sel_hi:[1,0,1]
	v_lshlrev_b32_e32 v26, 16, v139
	v_and_b32_e32 v27, 0xffff0000, v139
	v_pk_fma_f32 v[24:25], v[24:25], v[218:219], v[26:27] op_sel_hi:[1,0,1]
	v_cvt_pk_bf16_f32 v22, v22, v23
	v_cvt_pk_bf16_f32 v23, v24, v25
	v_lshlrev_b32_e32 v24, 16, v140
	v_and_b32_e32 v25, 0xffff0000, v140
	v_pk_fma_f32 v[18:19], v[18:19], v[218:219], v[24:25] op_sel_hi:[1,0,1]
	v_add_f32_e32 v82, v92, v82
	v_cvt_pk_bf16_f32 v24, v18, v19
	v_lshlrev_b32_e32 v18, 16, v141
	v_and_b32_e32 v19, 0xffff0000, v141
	v_pk_fma_f32 v[18:19], v[20:21], v[218:219], v[18:19] op_sel_hi:[1,0,1]
	v_and_b32_e32 v21, 0xffff0000, v23
	v_cvt_pk_bf16_f32 v25, v18, v19
	v_and_b32_e32 v19, 0xffff0000, v22
	v_lshlrev_b32_e32 v18, 16, v22
	v_mul_f32_e32 v19, v19, v19
	v_lshlrev_b32_e32 v20, 16, v23
	v_fmac_f32_e32 v19, v18, v18
	v_mul_f32_e32 v18, v21, v21
	global_store_dwordx4 v[34:35], v[22:25], off offset:256
	v_fmac_f32_e32 v18, v20, v20
	v_add_f32_e32 v18, v19, v18
	v_lshlrev_b32_e32 v22, 16, v24
	v_and_b32_e32 v23, 0xffff0000, v24
	v_lshlrev_b32_e32 v24, 16, v25
	v_and_b32_e32 v25, 0xffff0000, v25
	v_mul_f32_e32 v19, v23, v23
	v_mul_f32_e32 v20, v25, v25
	v_fmac_f32_e32 v19, v22, v22
	v_fmac_f32_e32 v20, v24, v24
	v_add_f32_e32 v19, v19, v20
	s_waitcnt vmcnt(15)
	v_lshlrev_b32_e32 v20, 16, v134
	v_and_b32_e32 v21, 0xffff0000, v134
	v_pk_fma_f32 v[14:15], v[14:15], v[194:195], v[20:21] op_sel_hi:[1,0,1]
	v_lshlrev_b32_e32 v20, 16, v135
	v_and_b32_e32 v21, 0xffff0000, v135
	v_pk_fma_f32 v[16:17], v[16:17], v[194:195], v[20:21] op_sel_hi:[1,0,1]
	v_cvt_pk_bf16_f32 v14, v14, v15
	v_cvt_pk_bf16_f32 v15, v16, v17
	v_lshlrev_b32_e32 v16, 16, v136
	v_and_b32_e32 v17, 0xffff0000, v136
	v_pk_fma_f32 v[10:11], v[10:11], v[194:195], v[16:17] op_sel_hi:[1,0,1]
	v_add_f32_e32 v18, v18, v19
	v_cvt_pk_bf16_f32 v16, v10, v11
	v_lshlrev_b32_e32 v10, 16, v137
	v_and_b32_e32 v11, 0xffff0000, v137
	v_pk_fma_f32 v[10:11], v[12:13], v[194:195], v[10:11] op_sel_hi:[1,0,1]
	v_add_f32_e32 v22, v28, v18
	v_cvt_pk_bf16_f32 v17, v10, v11
	v_and_b32_e32 v11, 0xffff0000, v14
	v_lshl_add_u64 v[18:19], s[86:87], 0, v[226:227]
	v_lshlrev_b32_e32 v10, 16, v14
	v_and_b32_e32 v13, 0xffff0000, v15
	v_mul_f32_e32 v11, v11, v11
	v_lshl_add_u64 v[18:19], v[18:19], 0, v[220:221]
	v_lshlrev_b32_e32 v12, 16, v15
	v_fmac_f32_e32 v11, v10, v10
	v_mul_f32_e32 v10, v13, v13
	global_store_dwordx4 v[18:19], v[14:17], off
	v_fmac_f32_e32 v10, v12, v12
	v_add_f32_e32 v10, v11, v10
	v_lshlrev_b32_e32 v14, 16, v16
	v_and_b32_e32 v15, 0xffff0000, v16
	v_lshlrev_b32_e32 v16, 16, v17
	v_and_b32_e32 v17, 0xffff0000, v17
	v_mul_f32_e32 v11, v15, v15
	v_mul_f32_e32 v12, v17, v17
	v_fmac_f32_e32 v11, v14, v14
	v_fmac_f32_e32 v12, v16, v16
	v_add_f32_e32 v11, v11, v12
	v_add_f32_e32 v12, v10, v11
	s_waitcnt vmcnt(15)
	v_lshlrev_b32_e32 v10, 16, v130
	v_and_b32_e32 v11, 0xffff0000, v130
	v_pk_fma_f32 v[6:7], v[6:7], v[194:195], v[10:11] op_sel_hi:[1,0,1]
	v_lshlrev_b32_e32 v10, 16, v131
	v_and_b32_e32 v11, 0xffff0000, v131
	v_pk_fma_f32 v[8:9], v[8:9], v[194:195], v[10:11] op_sel_hi:[1,0,1]
	v_cvt_pk_bf16_f32 v6, v6, v7
	v_cvt_pk_bf16_f32 v7, v8, v9
	v_lshlrev_b32_e32 v8, 16, v132
	v_and_b32_e32 v9, 0xffff0000, v132
	v_pk_fma_f32 v[2:3], v[2:3], v[194:195], v[8:9] op_sel_hi:[1,0,1]
	s_nop 0
	v_cvt_pk_bf16_f32 v8, v2, v3
	v_lshlrev_b32_e32 v2, 16, v133
	v_and_b32_e32 v3, 0xffff0000, v133
	v_pk_fma_f32 v[2:3], v[4:5], v[194:195], v[2:3] op_sel_hi:[1,0,1]
	v_and_b32_e32 v5, 0xffff0000, v7
	v_cvt_pk_bf16_f32 v9, v2, v3
	v_and_b32_e32 v3, 0xffff0000, v6
	v_lshlrev_b32_e32 v2, 16, v6
	v_mul_f32_e32 v3, v3, v3
	v_lshlrev_b32_e32 v4, 16, v7
	v_fmac_f32_e32 v3, v2, v2
	v_mul_f32_e32 v2, v5, v5
	global_store_dwordx4 v[18:19], v[6:9], off offset:256
	v_fmac_f32_e32 v2, v4, v4
	v_add_f32_e32 v2, v3, v2
	v_lshlrev_b32_e32 v6, 16, v8
	v_and_b32_e32 v7, 0xffff0000, v8
	v_lshlrev_b32_e32 v8, 16, v9
	v_and_b32_e32 v9, 0xffff0000, v9
	v_mul_f32_e32 v3, v7, v7
	v_mul_f32_e32 v4, v9, v9
	v_fmac_f32_e32 v3, v6, v6
	v_fmac_f32_e32 v4, v8, v8
	v_add_f32_e32 v3, v3, v4
	v_add_f32_e32 v2, v2, v3
	v_add_f32_e32 v8, v12, v2
	v_mov_b32_e32 v2, v0
	s_nop 0
	v_lshlrev_b32_e32 v10, 2, v2
	v_bitop3_b32 v2, v10, 64, v196 bitop3:0x6c
	ds_bpermute_b32 v3, v2, v114
	ds_bpermute_b32 v4, v2, v98
	ds_bpermute_b32 v5, v2, v82
	ds_bpermute_b32 v6, v2, v70
	ds_bpermute_b32 v7, v2, v54
	ds_bpermute_b32 v9, v2, v38
	ds_bpermute_b32 v11, v2, v22
	ds_bpermute_b32 v12, v2, v8
	s_waitcnt lgkmcnt(7)
	v_add_f32_e32 v2, v114, v3
	s_waitcnt lgkmcnt(6)
	v_add_f32_e32 v3, v98, v4
	s_waitcnt lgkmcnt(5)
	v_add_f32_e32 v4, v82, v5
	s_waitcnt lgkmcnt(4)
	v_add_f32_e32 v5, v70, v6
	s_waitcnt lgkmcnt(3)
	v_add_f32_e32 v6, v54, v7
	s_waitcnt lgkmcnt(2)
	v_add_f32_e32 v7, v38, v9
	s_waitcnt lgkmcnt(1)
	v_add_f32_e32 v9, v22, v11
	s_waitcnt lgkmcnt(0)
	v_add_f32_e32 v11, v8, v12
	v_bitop3_b32 v17, v10, s17, v196 bitop3:0x6c
	ds_bpermute_b32 v8, v17, v2
	ds_bpermute_b32 v10, v17, v3
	ds_bpermute_b32 v12, v17, v4
	ds_bpermute_b32 v13, v17, v5
	ds_bpermute_b32 v14, v17, v6
	ds_bpermute_b32 v15, v17, v7
	ds_bpermute_b32 v16, v17, v9
	ds_bpermute_b32 v17, v17, v11
	s_and_saveexec_b64 s[20:21], s[2:3]
	s_cbranch_execz .LBB0_775
	s_waitcnt lgkmcnt(5)
	v_add_f32_e32 v12, v4, v12
	v_add_f32_e32 v4, v2, v8
	s_mov_b32 s17, 0x49800000
	v_fma_f32 v4, v4, s17, 0.5
	v_trunc_f32_e32 v4, v4
	s_waitcnt lgkmcnt(4)
	v_add_f32_e32 v13, v5, v13
	v_mul_f32_e32 v5, 0x2f800000, v4
	v_floor_f32_e32 v5, v5
	v_fmac_f32_e32 v4, 0xcf800000, v5
	v_cvt_u32_f32_e32 v4, v4
	v_cvt_u32_f32_e32 v5, v5
	v_add_f32_e32 v10, v3, v10
	v_lshl_add_u64 v[2:3], v[216:217], 3, s[80:81]
	s_waitcnt lgkmcnt(3)
	v_add_f32_e32 v6, v6, v14
	global_atomic_add_x2 v[2:3], v[4:5], off
	v_fma_f32 v4, v10, s17, 0.5
	v_trunc_f32_e32 v4, v4
	v_mul_f32_e32 v5, 0x2f800000, v4
	v_floor_f32_e32 v5, v5
	v_fmac_f32_e32 v4, 0xcf800000, v5
	v_cvt_u32_f32_e32 v4, v4
	v_cvt_u32_f32_e32 v5, v5
	s_waitcnt lgkmcnt(2)
	v_add_f32_e32 v7, v7, v15
	s_waitcnt lgkmcnt(1)
	v_add_f32_e32 v9, v9, v16
	s_waitcnt lgkmcnt(0)
	v_add_f32_e32 v11, v11, v17
	global_atomic_add_x2 v[2:3], v[4:5], off offset:128
	v_fma_f32 v4, v12, s17, 0.5
	v_trunc_f32_e32 v4, v4
	v_mul_f32_e32 v5, 0x2f800000, v4
	v_floor_f32_e32 v5, v5
	v_fmac_f32_e32 v4, 0xcf800000, v5
	v_cvt_u32_f32_e32 v4, v4
	v_cvt_u32_f32_e32 v5, v5
	global_atomic_add_x2 v[2:3], v[4:5], off offset:256
	v_fma_f32 v4, v13, s17, 0.5
	v_trunc_f32_e32 v4, v4
	v_mul_f32_e32 v5, 0x2f800000, v4
	v_floor_f32_e32 v5, v5
	v_fmac_f32_e32 v4, 0xcf800000, v5
	v_cvt_u32_f32_e32 v4, v4
	v_cvt_u32_f32_e32 v5, v5
	global_atomic_add_x2 v[2:3], v[4:5], off offset:384
	v_fma_f32 v4, v6, s17, 0.5
	v_trunc_f32_e32 v4, v4
	v_mul_f32_e32 v5, 0x2f800000, v4
	v_floor_f32_e32 v5, v5
	v_fmac_f32_e32 v4, 0xcf800000, v5
	v_cvt_u32_f32_e32 v4, v4
	v_cvt_u32_f32_e32 v5, v5
	global_atomic_add_x2 v[2:3], v[4:5], off offset:1024
	v_fma_f32 v4, v7, s17, 0.5
	v_trunc_f32_e32 v4, v4
	v_mul_f32_e32 v5, 0x2f800000, v4
	v_floor_f32_e32 v5, v5
	v_fmac_f32_e32 v4, 0xcf800000, v5
	v_cvt_u32_f32_e32 v4, v4
	v_cvt_u32_f32_e32 v5, v5
	global_atomic_add_x2 v[2:3], v[4:5], off offset:1152
	v_fma_f32 v4, v9, s17, 0.5
	v_trunc_f32_e32 v4, v4
	v_mul_f32_e32 v5, 0x2f800000, v4
	v_floor_f32_e32 v5, v5
	v_fmac_f32_e32 v4, 0xcf800000, v5
	v_cvt_u32_f32_e32 v4, v4
	v_cvt_u32_f32_e32 v5, v5
	global_atomic_add_x2 v[2:3], v[4:5], off offset:1280
	v_fma_f32 v4, v11, s17, 0.5
	v_trunc_f32_e32 v4, v4
	v_mul_f32_e32 v5, 0x2f800000, v4
	v_floor_f32_e32 v5, v5
	v_fmac_f32_e32 v4, 0xcf800000, v5
	v_cvt_u32_f32_e32 v4, v4
	v_cvt_u32_f32_e32 v5, v5
	global_atomic_add_x2 v[2:3], v[4:5], off offset:1408

.Lalign_l5:
	s_movk_i32 s18, 0x80
	s_waitcnt vmcnt(15)
	v_lshlrev_b32_e32 v236, 16, v190
	v_and_b32_e32 v237, 0xffff0000, v190
	v_lshlrev_b32_e32 v190, 16, v191
	v_and_b32_e32 v191, 0xffff0000, v191
	v_pk_add_f32 v[186:187], v[186:187], v[236:237]
	v_pk_add_f32 v[188:189], v[188:189], v[190:191]
	v_cvt_pk_bf16_f32 v186, v186, v187
	v_cvt_pk_bf16_f32 v187, v188, v189
	v_lshlrev_b32_e32 v188, 16, v192
	v_and_b32_e32 v189, 0xffff0000, v192
	v_pk_add_f32 v[182:183], v[182:183], v[188:189]
	s_nop 0
	v_cvt_pk_bf16_f32 v188, v182, v183
	v_lshlrev_b32_e32 v182, 16, v193
	v_and_b32_e32 v183, 0xffff0000, v193
	v_pk_add_f32 v[182:183], v[184:185], v[182:183]
	v_and_b32_e32 v185, 0xffff0000, v187
	v_cvt_pk_bf16_f32 v189, v182, v183
	v_and_b32_e32 v183, 0xffff0000, v186
	v_lshlrev_b32_e32 v182, 16, v186
	v_mul_f32_e32 v183, v183, v183
	v_lshlrev_b32_e32 v184, 16, v187
	v_fmac_f32_e32 v183, v182, v182
	v_mul_f32_e32 v182, v185, v185
	global_store_dwordx4 v[232:233], v[186:189], off
	v_fmac_f32_e32 v182, v184, v184
	v_add_f32_e32 v182, v183, v182
	v_lshlrev_b32_e32 v186, 16, v188
	v_and_b32_e32 v187, 0xffff0000, v188
	v_lshlrev_b32_e32 v188, 16, v189
	v_and_b32_e32 v189, 0xffff0000, v189
	v_mul_f32_e32 v183, v187, v187
	v_mul_f32_e32 v184, v189, v189
	v_fmac_f32_e32 v183, v186, v186
	v_fmac_f32_e32 v184, v188, v188
	v_add_f32_e32 v183, v183, v184
	v_add_f32_e32 v184, v182, v183
	s_waitcnt vmcnt(15)
	v_lshlrev_b32_e32 v182, 16, v178
	v_and_b32_e32 v183, 0xffff0000, v178
	v_lshlrev_b32_e32 v178, 16, v179
	v_and_b32_e32 v179, 0xffff0000, v179
	v_pk_add_f32 v[166:167], v[166:167], v[182:183]
	v_pk_add_f32 v[168:169], v[168:169], v[178:179]
	v_cvt_pk_bf16_f32 v166, v166, v167
	v_cvt_pk_bf16_f32 v167, v168, v169
	v_lshlrev_b32_e32 v168, 16, v180
	v_and_b32_e32 v169, 0xffff0000, v180
	v_pk_add_f32 v[146:147], v[146:147], v[168:169]
	s_nop 0
	v_cvt_pk_bf16_f32 v168, v146, v147
	v_lshlrev_b32_e32 v146, 16, v181
	v_and_b32_e32 v147, 0xffff0000, v181
	v_pk_add_f32 v[146:147], v[148:149], v[146:147]
	v_and_b32_e32 v149, 0xffff0000, v167
	v_cvt_pk_bf16_f32 v169, v146, v147
	v_and_b32_e32 v147, 0xffff0000, v166
	v_lshlrev_b32_e32 v146, 16, v166
	v_mul_f32_e32 v147, v147, v147
	v_lshlrev_b32_e32 v148, 16, v167
	v_fmac_f32_e32 v147, v146, v146
	v_mul_f32_e32 v146, v149, v149
	global_store_dwordx4 v[232:233], v[166:169], off offset:256
	v_fmac_f32_e32 v146, v148, v148
	v_add_f32_e32 v146, v147, v146
	v_and_b32_e32 v167, 0xffff0000, v168
	v_lshlrev_b32_e32 v166, 16, v168
	v_mul_f32_e32 v147, v167, v167
	v_fmac_f32_e32 v147, v166, v166
	s_waitcnt vmcnt(15)
	v_lshlrev_b32_e32 v166, 16, v174
	v_and_b32_e32 v167, 0xffff0000, v174
	v_pk_add_f32 v[138:139], v[138:139], v[166:167]
	v_lshlrev_b32_e32 v166, 16, v175
	v_and_b32_e32 v167, 0xffff0000, v175
	v_pk_add_f32 v[140:141], v[140:141], v[166:167]
	v_cvt_pk_bf16_f32 v138, v138, v139
	v_cvt_pk_bf16_f32 v139, v140, v141
	v_lshlrev_b32_e32 v140, 16, v176
	v_and_b32_e32 v141, 0xffff0000, v176
	v_pk_add_f32 v[134:135], v[134:135], v[140:141]
	v_lshlrev_b32_e32 v168, 16, v169
	v_and_b32_e32 v169, 0xffff0000, v169
	v_cvt_pk_bf16_f32 v140, v134, v135
	v_lshlrev_b32_e32 v134, 16, v177
	v_and_b32_e32 v135, 0xffff0000, v177
	v_mul_f32_e32 v148, v169, v169
	v_pk_add_f32 v[134:135], v[136:137], v[134:135]
	v_fmac_f32_e32 v148, v168, v168
	v_cvt_pk_bf16_f32 v141, v134, v135
	v_and_b32_e32 v135, 0xffff0000, v138
	v_add_f32_e32 v147, v147, v148
	v_lshl_add_u64 v[148:149], s[86:87], 0, v[230:231]
	v_lshlrev_b32_e32 v134, 16, v138
	v_and_b32_e32 v137, 0xffff0000, v139
	v_mul_f32_e32 v135, v135, v135
	v_lshl_add_u64 v[148:149], v[148:149], 0, v[216:217]
	v_lshlrev_b32_e32 v136, 16, v139
	v_fmac_f32_e32 v135, v134, v134
	v_mul_f32_e32 v134, v137, v137
	global_store_dwordx4 v[148:149], v[138:141], off
	v_fmac_f32_e32 v134, v136, v136
	v_add_f32_e32 v134, v135, v134
	v_lshlrev_b32_e32 v138, 16, v140
	v_and_b32_e32 v139, 0xffff0000, v140
	v_lshlrev_b32_e32 v140, 16, v141
	v_and_b32_e32 v141, 0xffff0000, v141
	v_mul_f32_e32 v135, v139, v139
	v_mul_f32_e32 v136, v141, v141
	v_fmac_f32_e32 v135, v138, v138
	v_fmac_f32_e32 v136, v140, v140
	v_add_f32_e32 v135, v135, v136
	v_add_f32_e32 v136, v134, v135
	s_waitcnt vmcnt(15)
	v_lshlrev_b32_e32 v134, 16, v170
	v_and_b32_e32 v135, 0xffff0000, v170
	v_pk_add_f32 v[126:127], v[126:127], v[134:135]
	v_lshlrev_b32_e32 v134, 16, v171
	v_and_b32_e32 v135, 0xffff0000, v171
	v_pk_add_f32 v[128:129], v[128:129], v[134:135]
	v_cvt_pk_bf16_f32 v126, v126, v127
	v_cvt_pk_bf16_f32 v127, v128, v129
	v_lshlrev_b32_e32 v128, 16, v172
	v_and_b32_e32 v129, 0xffff0000, v172
	v_pk_add_f32 v[122:123], v[122:123], v[128:129]
	v_add_f32_e32 v146, v146, v147
	v_cvt_pk_bf16_f32 v128, v122, v123
	v_lshlrev_b32_e32 v122, 16, v173
	v_and_b32_e32 v123, 0xffff0000, v173
	v_pk_add_f32 v[122:123], v[124:125], v[122:123]
	v_and_b32_e32 v125, 0xffff0000, v127
	v_cvt_pk_bf16_f32 v129, v122, v123
	v_and_b32_e32 v123, 0xffff0000, v126
	v_lshlrev_b32_e32 v122, 16, v126
	v_mul_f32_e32 v123, v123, v123
	v_lshlrev_b32_e32 v124, 16, v127
	v_fmac_f32_e32 v123, v122, v122
	v_mul_f32_e32 v122, v125, v125
	global_store_dwordx4 v[148:149], v[126:129], off offset:256
	v_fmac_f32_e32 v122, v124, v124
	v_add_f32_e32 v122, v123, v122
	v_and_b32_e32 v127, 0xffff0000, v128
	v_lshlrev_b32_e32 v126, 16, v128
	v_mul_f32_e32 v123, v127, v127
	v_fmac_f32_e32 v123, v126, v126
	s_waitcnt vmcnt(15)
	v_lshlrev_b32_e32 v126, 16, v162
	v_and_b32_e32 v127, 0xffff0000, v162
	v_pk_add_f32 v[114:115], v[114:115], v[126:127]
	v_lshlrev_b32_e32 v126, 16, v163
	v_and_b32_e32 v127, 0xffff0000, v163
	v_pk_add_f32 v[116:117], v[116:117], v[126:127]
	v_cvt_pk_bf16_f32 v114, v114, v115
	v_cvt_pk_bf16_f32 v115, v116, v117
	v_lshlrev_b32_e32 v116, 16, v164
	v_and_b32_e32 v117, 0xffff0000, v164
	v_pk_add_f32 v[110:111], v[110:111], v[116:117]
	v_lshlrev_b32_e32 v128, 16, v129
	v_and_b32_e32 v129, 0xffff0000, v129
	v_cvt_pk_bf16_f32 v116, v110, v111
	v_lshlrev_b32_e32 v110, 16, v165
	v_and_b32_e32 v111, 0xffff0000, v165
	v_mul_f32_e32 v124, v129, v129
	v_pk_add_f32 v[110:111], v[112:113], v[110:111]
	v_fmac_f32_e32 v124, v128, v128
	v_cvt_pk_bf16_f32 v117, v110, v111
	v_and_b32_e32 v111, 0xffff0000, v114
	v_add_f32_e32 v123, v123, v124
	v_lshl_add_u64 v[124:125], s[86:87], 0, v[228:229]
	v_lshlrev_b32_e32 v110, 16, v114
	v_and_b32_e32 v113, 0xffff0000, v115
	v_mul_f32_e32 v111, v111, v111
	v_lshl_add_u64 v[124:125], v[124:125], 0, v[216:217]
	v_lshlrev_b32_e32 v112, 16, v115
	v_fmac_f32_e32 v111, v110, v110
	v_mul_f32_e32 v110, v113, v113
	global_store_dwordx4 v[124:125], v[114:117], off
	v_fmac_f32_e32 v110, v112, v112
	v_add_f32_e32 v110, v111, v110
	v_lshlrev_b32_e32 v114, 16, v116
	v_and_b32_e32 v115, 0xffff0000, v116
	v_lshlrev_b32_e32 v116, 16, v117
	v_and_b32_e32 v117, 0xffff0000, v117
	v_mul_f32_e32 v111, v115, v115
	v_mul_f32_e32 v112, v117, v117
	v_fmac_f32_e32 v111, v114, v114
	v_fmac_f32_e32 v112, v116, v116
	v_add_f32_e32 v111, v111, v112
	v_add_f32_e32 v112, v110, v111
	s_waitcnt vmcnt(15)
	v_lshlrev_b32_e32 v110, 16, v158
	v_and_b32_e32 v111, 0xffff0000, v158
	v_pk_add_f32 v[102:103], v[102:103], v[110:111]
	v_lshlrev_b32_e32 v110, 16, v159
	v_and_b32_e32 v111, 0xffff0000, v159
	v_pk_add_f32 v[104:105], v[104:105], v[110:111]
	v_cvt_pk_bf16_f32 v102, v102, v103
	v_cvt_pk_bf16_f32 v103, v104, v105
	v_lshlrev_b32_e32 v104, 16, v160
	v_and_b32_e32 v105, 0xffff0000, v160
	v_pk_add_f32 v[94:95], v[94:95], v[104:105]
	v_add_f32_e32 v122, v122, v123
	v_cvt_pk_bf16_f32 v104, v94, v95
	v_lshlrev_b32_e32 v94, 16, v161
	v_and_b32_e32 v95, 0xffff0000, v161
	v_pk_add_f32 v[94:95], v[96:97], v[94:95]
	v_and_b32_e32 v97, 0xffff0000, v103
	v_cvt_pk_bf16_f32 v105, v94, v95
	v_and_b32_e32 v95, 0xffff0000, v102
	v_lshlrev_b32_e32 v94, 16, v102
	v_mul_f32_e32 v95, v95, v95
	v_lshlrev_b32_e32 v96, 16, v103
	v_fmac_f32_e32 v95, v94, v94
	v_mul_f32_e32 v94, v97, v97
	global_store_dwordx4 v[124:125], v[102:105], off offset:256
	v_fmac_f32_e32 v94, v96, v96
	v_add_f32_e32 v94, v95, v94
	v_and_b32_e32 v103, 0xffff0000, v104
	v_lshlrev_b32_e32 v102, 16, v104
	v_mul_f32_e32 v95, v103, v103
	v_fmac_f32_e32 v95, v102, v102
	s_waitcnt vmcnt(15)
	v_lshlrev_b32_e32 v102, 16, v154
	v_and_b32_e32 v103, 0xffff0000, v154
	v_pk_add_f32 v[90:91], v[90:91], v[102:103]
	v_lshlrev_b32_e32 v102, 16, v155
	v_and_b32_e32 v103, 0xffff0000, v155
	v_pk_add_f32 v[92:93], v[92:93], v[102:103]
	v_cvt_pk_bf16_f32 v90, v90, v91
	v_cvt_pk_bf16_f32 v91, v92, v93
	v_lshlrev_b32_e32 v92, 16, v156
	v_and_b32_e32 v93, 0xffff0000, v156
	v_pk_add_f32 v[86:87], v[86:87], v[92:93]
	v_lshlrev_b32_e32 v104, 16, v105
	v_and_b32_e32 v105, 0xffff0000, v105
	v_cvt_pk_bf16_f32 v92, v86, v87
	v_lshlrev_b32_e32 v86, 16, v157
	v_and_b32_e32 v87, 0xffff0000, v157
	v_mul_f32_e32 v96, v105, v105
	v_pk_add_f32 v[86:87], v[88:89], v[86:87]
	v_fmac_f32_e32 v96, v104, v104
	v_cvt_pk_bf16_f32 v93, v86, v87
	v_and_b32_e32 v87, 0xffff0000, v90
	v_add_f32_e32 v95, v95, v96
	v_lshl_add_u64 v[96:97], s[86:87], 0, v[226:227]
	v_lshlrev_b32_e32 v86, 16, v90
	v_and_b32_e32 v89, 0xffff0000, v91
	v_mul_f32_e32 v87, v87, v87
	v_lshl_add_u64 v[96:97], v[96:97], 0, v[216:217]
	v_lshlrev_b32_e32 v88, 16, v91
	v_fmac_f32_e32 v87, v86, v86
	v_mul_f32_e32 v86, v89, v89
	global_store_dwordx4 v[96:97], v[90:93], off
	v_fmac_f32_e32 v86, v88, v88
	v_add_f32_e32 v86, v87, v86
	v_lshlrev_b32_e32 v90, 16, v92
	v_and_b32_e32 v91, 0xffff0000, v92
	v_lshlrev_b32_e32 v92, 16, v93
	v_and_b32_e32 v93, 0xffff0000, v93
	v_mul_f32_e32 v87, v91, v91
	v_mul_f32_e32 v88, v93, v93
	v_fmac_f32_e32 v87, v90, v90
	v_fmac_f32_e32 v88, v92, v92
	v_add_f32_e32 v87, v87, v88
	v_add_f32_e32 v88, v86, v87
	s_waitcnt vmcnt(15)
	v_lshlrev_b32_e32 v86, 16, v150
	v_and_b32_e32 v87, 0xffff0000, v150
	v_pk_add_f32 v[74:75], v[74:75], v[86:87]
	v_lshlrev_b32_e32 v86, 16, v151
	v_and_b32_e32 v87, 0xffff0000, v151
	v_pk_add_f32 v[76:77], v[76:77], v[86:87]
	v_cvt_pk_bf16_f32 v74, v74, v75
	v_cvt_pk_bf16_f32 v75, v76, v77
	v_lshlrev_b32_e32 v76, 16, v152
	v_and_b32_e32 v77, 0xffff0000, v152
	v_pk_add_f32 v[70:71], v[70:71], v[76:77]
	v_add_f32_e32 v94, v94, v95
	v_cvt_pk_bf16_f32 v76, v70, v71
	v_lshlrev_b32_e32 v70, 16, v153
	v_and_b32_e32 v71, 0xffff0000, v153
	v_pk_add_f32 v[70:71], v[72:73], v[70:71]
	v_and_b32_e32 v73, 0xffff0000, v75
	v_cvt_pk_bf16_f32 v77, v70, v71
	v_and_b32_e32 v71, 0xffff0000, v74
	v_lshlrev_b32_e32 v70, 16, v74
	v_mul_f32_e32 v71, v71, v71
	v_lshlrev_b32_e32 v72, 16, v75
	v_fmac_f32_e32 v71, v70, v70
	v_mul_f32_e32 v70, v73, v73
	global_store_dwordx4 v[96:97], v[74:77], off offset:256
	v_fmac_f32_e32 v70, v72, v72
	v_add_f32_e32 v70, v71, v70
	v_lshlrev_b32_e32 v74, 16, v76
	v_and_b32_e32 v75, 0xffff0000, v76
	v_lshlrev_b32_e32 v76, 16, v77
	v_and_b32_e32 v77, 0xffff0000, v77
	v_mul_f32_e32 v71, v75, v75
	v_mul_f32_e32 v72, v77, v77
	v_fmac_f32_e32 v71, v74, v74
	v_fmac_f32_e32 v72, v76, v76
	v_add_f32_e32 v71, v71, v72
	s_waitcnt vmcnt(15)
	v_lshlrev_b32_e32 v72, 16, v142
	v_and_b32_e32 v73, 0xffff0000, v142
	v_pk_add_f32 v[62:63], v[62:63], v[72:73]
	v_lshlrev_b32_e32 v72, 16, v143
	v_and_b32_e32 v73, 0xffff0000, v143
	v_pk_add_f32 v[64:65], v[64:65], v[72:73]
	v_cvt_pk_bf16_f32 v62, v62, v63
	v_cvt_pk_bf16_f32 v63, v64, v65
	v_lshlrev_b32_e32 v64, 16, v144
	v_and_b32_e32 v65, 0xffff0000, v144
	v_pk_add_f32 v[58:59], v[58:59], v[64:65]
	v_add_f32_e32 v70, v70, v71
	v_cvt_pk_bf16_f32 v64, v58, v59
	v_lshlrev_b32_e32 v58, 16, v145
	v_and_b32_e32 v59, 0xffff0000, v145
	v_pk_add_f32 v[58:59], v[60:61], v[58:59]
	v_add_f32_e32 v74, v88, v70
	v_cvt_pk_bf16_f32 v65, v58, v59
	v_and_b32_e32 v59, 0xffff0000, v62
	v_lshl_add_u64 v[70:71], s[86:87], 0, v[224:225]
	v_lshlrev_b32_e32 v58, 16, v62
	v_and_b32_e32 v61, 0xffff0000, v63
	v_mul_f32_e32 v59, v59, v59
	v_lshl_add_u64 v[70:71], v[70:71], 0, v[216:217]
	v_lshlrev_b32_e32 v60, 16, v63
	v_fmac_f32_e32 v59, v58, v58
	v_mul_f32_e32 v58, v61, v61
	global_store_dwordx4 v[70:71], v[62:65], off
	v_fmac_f32_e32 v58, v60, v60
	v_add_f32_e32 v58, v59, v58
	v_lshlrev_b32_e32 v62, 16, v64
	v_and_b32_e32 v63, 0xffff0000, v64
	v_lshlrev_b32_e32 v64, 16, v65
	v_and_b32_e32 v65, 0xffff0000, v65
	v_mul_f32_e32 v59, v63, v63
	v_mul_f32_e32 v60, v65, v65
	v_fmac_f32_e32 v59, v62, v62
	v_fmac_f32_e32 v60, v64, v64
	v_add_f32_e32 v59, v59, v60
	v_add_f32_e32 v60, v58, v59
	s_waitcnt vmcnt(15)
	v_lshlrev_b32_e32 v58, 16, v130
	v_and_b32_e32 v59, 0xffff0000, v130
	v_pk_add_f32 v[54:55], v[54:55], v[58:59]
	v_lshlrev_b32_e32 v58, 16, v131
	v_and_b32_e32 v59, 0xffff0000, v131
	v_pk_add_f32 v[56:57], v[56:57], v[58:59]
	v_cvt_pk_bf16_f32 v54, v54, v55
	v_cvt_pk_bf16_f32 v55, v56, v57
	v_lshlrev_b32_e32 v56, 16, v132
	v_and_b32_e32 v57, 0xffff0000, v132
	v_pk_add_f32 v[50:51], v[50:51], v[56:57]
	v_add_f32_e32 v146, v184, v146
	v_cvt_pk_bf16_f32 v56, v50, v51
	v_lshlrev_b32_e32 v50, 16, v133
	v_and_b32_e32 v51, 0xffff0000, v133
	v_pk_add_f32 v[50:51], v[52:53], v[50:51]
	v_and_b32_e32 v53, 0xffff0000, v55
	v_cvt_pk_bf16_f32 v57, v50, v51
	v_and_b32_e32 v51, 0xffff0000, v54
	v_lshlrev_b32_e32 v50, 16, v54
	v_mul_f32_e32 v51, v51, v51
	v_lshlrev_b32_e32 v52, 16, v55
	v_fmac_f32_e32 v51, v50, v50
	v_mul_f32_e32 v50, v53, v53
	global_store_dwordx4 v[70:71], v[54:57], off offset:256
	v_fmac_f32_e32 v50, v52, v52
	v_add_f32_e32 v50, v51, v50
	v_lshlrev_b32_e32 v54, 16, v56
	v_and_b32_e32 v55, 0xffff0000, v56
	v_lshlrev_b32_e32 v56, 16, v57
	v_and_b32_e32 v57, 0xffff0000, v57
	v_mul_f32_e32 v51, v55, v55
	v_mul_f32_e32 v52, v57, v57
	v_fmac_f32_e32 v51, v54, v54
	v_fmac_f32_e32 v52, v56, v56
	v_add_f32_e32 v51, v51, v52
	s_waitcnt vmcnt(15)
	v_lshlrev_b32_e32 v52, 16, v118
	v_and_b32_e32 v53, 0xffff0000, v118
	v_pk_add_f32 v[46:47], v[46:47], v[52:53]
	v_lshlrev_b32_e32 v52, 16, v119
	v_and_b32_e32 v53, 0xffff0000, v119
	v_pk_add_f32 v[48:49], v[48:49], v[52:53]
	v_cvt_pk_bf16_f32 v46, v46, v47
	v_cvt_pk_bf16_f32 v47, v48, v49
	v_lshlrev_b32_e32 v48, 16, v120
	v_and_b32_e32 v49, 0xffff0000, v120
	v_pk_add_f32 v[42:43], v[42:43], v[48:49]
	v_add_f32_e32 v50, v50, v51
	v_cvt_pk_bf16_f32 v48, v42, v43
	v_lshlrev_b32_e32 v42, 16, v121
	v_and_b32_e32 v43, 0xffff0000, v121
	v_pk_add_f32 v[42:43], v[44:45], v[42:43]
	v_add_f32_e32 v54, v60, v50
	v_cvt_pk_bf16_f32 v49, v42, v43
	v_and_b32_e32 v43, 0xffff0000, v46
	v_lshl_add_u64 v[50:51], s[86:87], 0, v[222:223]
	v_lshlrev_b32_e32 v42, 16, v46
	v_and_b32_e32 v45, 0xffff0000, v47
	v_mul_f32_e32 v43, v43, v43
	v_lshl_add_u64 v[50:51], v[50:51], 0, v[216:217]
	v_lshlrev_b32_e32 v44, 16, v47
	v_fmac_f32_e32 v43, v42, v42
	v_mul_f32_e32 v42, v45, v45
	global_store_dwordx4 v[50:51], v[46:49], off
	v_fmac_f32_e32 v42, v44, v44
	v_add_f32_e32 v42, v43, v42
	v_lshlrev_b32_e32 v46, 16, v48
	v_and_b32_e32 v47, 0xffff0000, v48
	v_lshlrev_b32_e32 v48, 16, v49
	v_and_b32_e32 v49, 0xffff0000, v49
	v_mul_f32_e32 v43, v47, v47
	v_mul_f32_e32 v44, v49, v49
	v_fmac_f32_e32 v43, v46, v46
	v_fmac_f32_e32 v44, v48, v48
	v_add_f32_e32 v43, v43, v44
	v_add_f32_e32 v44, v42, v43
	s_waitcnt vmcnt(15)
	v_lshlrev_b32_e32 v42, 16, v106
	v_and_b32_e32 v43, 0xffff0000, v106
	v_pk_add_f32 v[38:39], v[38:39], v[42:43]
	v_lshlrev_b32_e32 v42, 16, v107
	v_and_b32_e32 v43, 0xffff0000, v107
	v_pk_add_f32 v[40:41], v[40:41], v[42:43]
	v_cvt_pk_bf16_f32 v38, v38, v39
	v_cvt_pk_bf16_f32 v39, v40, v41
	v_lshlrev_b32_e32 v40, 16, v108
	v_and_b32_e32 v41, 0xffff0000, v108
	v_pk_add_f32 v[34:35], v[34:35], v[40:41]
	v_add_f32_e32 v122, v136, v122
	v_cvt_pk_bf16_f32 v40, v34, v35
	v_lshlrev_b32_e32 v34, 16, v109
	v_and_b32_e32 v35, 0xffff0000, v109
	v_pk_add_f32 v[34:35], v[36:37], v[34:35]
	v_and_b32_e32 v37, 0xffff0000, v39
	v_cvt_pk_bf16_f32 v41, v34, v35
	v_and_b32_e32 v35, 0xffff0000, v38
	v_lshlrev_b32_e32 v34, 16, v38
	v_mul_f32_e32 v35, v35, v35
	v_lshlrev_b32_e32 v36, 16, v39
	v_fmac_f32_e32 v35, v34, v34
	v_mul_f32_e32 v34, v37, v37
	global_store_dwordx4 v[50:51], v[38:41], off offset:256
	v_fmac_f32_e32 v34, v36, v36
	v_add_f32_e32 v34, v35, v34
	v_lshlrev_b32_e32 v38, 16, v40
	v_and_b32_e32 v39, 0xffff0000, v40
	v_lshlrev_b32_e32 v40, 16, v41
	v_and_b32_e32 v41, 0xffff0000, v41
	v_mul_f32_e32 v35, v39, v39
	v_mul_f32_e32 v36, v41, v41
	v_fmac_f32_e32 v35, v38, v38
	v_fmac_f32_e32 v36, v40, v40
	v_add_f32_e32 v35, v35, v36
	s_waitcnt vmcnt(15)
	v_lshlrev_b32_e32 v36, 16, v98
	v_and_b32_e32 v37, 0xffff0000, v98
	v_pk_add_f32 v[30:31], v[30:31], v[36:37]
	v_lshlrev_b32_e32 v36, 16, v99
	v_and_b32_e32 v37, 0xffff0000, v99
	v_pk_add_f32 v[32:33], v[32:33], v[36:37]
	v_cvt_pk_bf16_f32 v30, v30, v31
	v_cvt_pk_bf16_f32 v31, v32, v33
	v_lshlrev_b32_e32 v32, 16, v100
	v_and_b32_e32 v33, 0xffff0000, v100
	v_pk_add_f32 v[26:27], v[26:27], v[32:33]
	v_add_f32_e32 v34, v34, v35
	v_cvt_pk_bf16_f32 v32, v26, v27
	v_lshlrev_b32_e32 v26, 16, v101
	v_and_b32_e32 v27, 0xffff0000, v101
	v_pk_add_f32 v[26:27], v[28:29], v[26:27]
	v_add_f32_e32 v38, v44, v34
	v_cvt_pk_bf16_f32 v33, v26, v27
	v_and_b32_e32 v27, 0xffff0000, v30
	v_lshl_add_u64 v[34:35], s[86:87], 0, v[220:221]
	v_lshlrev_b32_e32 v26, 16, v30
	v_and_b32_e32 v29, 0xffff0000, v31
	v_mul_f32_e32 v27, v27, v27
	v_lshl_add_u64 v[34:35], v[34:35], 0, v[216:217]
	v_lshlrev_b32_e32 v28, 16, v31
	v_fmac_f32_e32 v27, v26, v26
	v_mul_f32_e32 v26, v29, v29
	global_store_dwordx4 v[34:35], v[30:33], off
	v_fmac_f32_e32 v26, v28, v28
	v_add_f32_e32 v26, v27, v26
	v_lshlrev_b32_e32 v30, 16, v32
	v_and_b32_e32 v31, 0xffff0000, v32
	v_lshlrev_b32_e32 v32, 16, v33
	v_and_b32_e32 v33, 0xffff0000, v33
	v_mul_f32_e32 v27, v31, v31
	v_mul_f32_e32 v28, v33, v33
	v_fmac_f32_e32 v27, v30, v30
	v_fmac_f32_e32 v28, v32, v32
	v_add_f32_e32 v27, v27, v28
	v_add_f32_e32 v28, v26, v27
	s_waitcnt vmcnt(15)
	v_lshlrev_b32_e32 v26, 16, v82
	v_and_b32_e32 v27, 0xffff0000, v82
	v_pk_add_f32 v[22:23], v[22:23], v[26:27]
	v_lshlrev_b32_e32 v26, 16, v83
	v_and_b32_e32 v27, 0xffff0000, v83
	v_pk_add_f32 v[24:25], v[24:25], v[26:27]
	v_cvt_pk_bf16_f32 v22, v22, v23
	v_cvt_pk_bf16_f32 v23, v24, v25
	v_lshlrev_b32_e32 v24, 16, v84
	v_and_b32_e32 v25, 0xffff0000, v84
	v_pk_add_f32 v[18:19], v[18:19], v[24:25]
	v_add_f32_e32 v94, v112, v94
	v_cvt_pk_bf16_f32 v24, v18, v19
	v_lshlrev_b32_e32 v18, 16, v85
	v_and_b32_e32 v19, 0xffff0000, v85
	v_pk_add_f32 v[18:19], v[20:21], v[18:19]
	v_and_b32_e32 v21, 0xffff0000, v23
	v_cvt_pk_bf16_f32 v25, v18, v19
	v_and_b32_e32 v19, 0xffff0000, v22
	v_lshlrev_b32_e32 v18, 16, v22
	v_mul_f32_e32 v19, v19, v19
	v_lshlrev_b32_e32 v20, 16, v23
	v_fmac_f32_e32 v19, v18, v18
	v_mul_f32_e32 v18, v21, v21
	global_store_dwordx4 v[34:35], v[22:25], off offset:256
	v_fmac_f32_e32 v18, v20, v20
	v_add_f32_e32 v18, v19, v18
	v_lshlrev_b32_e32 v22, 16, v24
	v_and_b32_e32 v23, 0xffff0000, v24
	v_lshlrev_b32_e32 v24, 16, v25
	v_and_b32_e32 v25, 0xffff0000, v25
	v_mul_f32_e32 v19, v23, v23
	v_mul_f32_e32 v20, v25, v25
	v_fmac_f32_e32 v19, v22, v22
	v_fmac_f32_e32 v20, v24, v24
	v_add_f32_e32 v19, v19, v20
	s_waitcnt vmcnt(15)
	v_lshlrev_b32_e32 v20, 16, v78
	v_and_b32_e32 v21, 0xffff0000, v78
	v_pk_add_f32 v[14:15], v[14:15], v[20:21]
	v_lshlrev_b32_e32 v20, 16, v79
	v_and_b32_e32 v21, 0xffff0000, v79
	v_pk_add_f32 v[16:17], v[16:17], v[20:21]
	v_cvt_pk_bf16_f32 v14, v14, v15
	v_cvt_pk_bf16_f32 v15, v16, v17
	v_lshlrev_b32_e32 v16, 16, v80
	v_and_b32_e32 v17, 0xffff0000, v80
	v_pk_add_f32 v[10:11], v[10:11], v[16:17]
	v_add_f32_e32 v18, v18, v19
	v_cvt_pk_bf16_f32 v16, v10, v11
	v_lshlrev_b32_e32 v10, 16, v81
	v_and_b32_e32 v11, 0xffff0000, v81
	v_pk_add_f32 v[10:11], v[12:13], v[10:11]
	v_add_f32_e32 v22, v28, v18
	v_cvt_pk_bf16_f32 v17, v10, v11
	v_and_b32_e32 v11, 0xffff0000, v14
	v_lshl_add_u64 v[18:19], s[86:87], 0, v[218:219]
	v_lshlrev_b32_e32 v10, 16, v14
	v_and_b32_e32 v13, 0xffff0000, v15
	v_mul_f32_e32 v11, v11, v11
	v_lshl_add_u64 v[18:19], v[18:19], 0, v[216:217]
	v_lshlrev_b32_e32 v12, 16, v15
	v_fmac_f32_e32 v11, v10, v10
	v_mul_f32_e32 v10, v13, v13
	global_store_dwordx4 v[18:19], v[14:17], off
	v_fmac_f32_e32 v10, v12, v12
	v_add_f32_e32 v10, v11, v10
	v_lshlrev_b32_e32 v14, 16, v16
	v_and_b32_e32 v15, 0xffff0000, v16
	v_lshlrev_b32_e32 v16, 16, v17
	v_and_b32_e32 v17, 0xffff0000, v17
	v_mul_f32_e32 v11, v15, v15
	v_mul_f32_e32 v12, v17, v17
	v_fmac_f32_e32 v11, v14, v14
	v_fmac_f32_e32 v12, v16, v16
	v_add_f32_e32 v11, v11, v12
	v_add_f32_e32 v12, v10, v11
	s_waitcnt vmcnt(15)
	v_lshlrev_b32_e32 v10, 16, v66
	v_and_b32_e32 v11, 0xffff0000, v66
	v_pk_add_f32 v[6:7], v[6:7], v[10:11]
	v_lshlrev_b32_e32 v10, 16, v67
	v_and_b32_e32 v11, 0xffff0000, v67
	v_pk_add_f32 v[8:9], v[8:9], v[10:11]
	v_cvt_pk_bf16_f32 v6, v6, v7
	v_cvt_pk_bf16_f32 v7, v8, v9
	v_lshlrev_b32_e32 v8, 16, v68
	v_and_b32_e32 v9, 0xffff0000, v68
	v_pk_add_f32 v[2:3], v[2:3], v[8:9]
	s_nop 0
	v_cvt_pk_bf16_f32 v8, v2, v3
	v_lshlrev_b32_e32 v2, 16, v69
	v_and_b32_e32 v3, 0xffff0000, v69
	v_pk_add_f32 v[2:3], v[4:5], v[2:3]
	v_and_b32_e32 v5, 0xffff0000, v7
	v_cvt_pk_bf16_f32 v9, v2, v3
	v_and_b32_e32 v3, 0xffff0000, v6
	v_lshlrev_b32_e32 v2, 16, v6
	v_mul_f32_e32 v3, v3, v3
	v_lshlrev_b32_e32 v4, 16, v7
	v_fmac_f32_e32 v3, v2, v2
	v_mul_f32_e32 v2, v5, v5
	global_store_dwordx4 v[18:19], v[6:9], off offset:256
	v_fmac_f32_e32 v2, v4, v4
	v_add_f32_e32 v2, v3, v2
	v_lshlrev_b32_e32 v6, 16, v8
	v_and_b32_e32 v7, 0xffff0000, v8
	v_lshlrev_b32_e32 v8, 16, v9
	v_and_b32_e32 v9, 0xffff0000, v9
	v_mul_f32_e32 v3, v7, v7
	v_mul_f32_e32 v4, v9, v9
	v_fmac_f32_e32 v3, v6, v6
	v_fmac_f32_e32 v4, v8, v8
	v_add_f32_e32 v3, v3, v4
	v_add_f32_e32 v2, v2, v3
	v_add_f32_e32 v8, v12, v2
	v_mov_b32_e32 v2, v0
	s_nop 0
	v_lshlrev_b32_e32 v10, 2, v2
	v_bitop3_b32 v2, v10, 64, v196 bitop3:0x6c
	ds_bpermute_b32 v3, v2, v146
	ds_bpermute_b32 v4, v2, v122
	ds_bpermute_b32 v5, v2, v94
	ds_bpermute_b32 v6, v2, v74
	ds_bpermute_b32 v7, v2, v54
	ds_bpermute_b32 v9, v2, v38
	ds_bpermute_b32 v11, v2, v22
	ds_bpermute_b32 v12, v2, v8
	s_waitcnt lgkmcnt(7)
	v_add_f32_e32 v2, v146, v3
	s_waitcnt lgkmcnt(6)
	v_add_f32_e32 v3, v122, v4
	s_waitcnt lgkmcnt(5)
	v_add_f32_e32 v4, v94, v5
	s_waitcnt lgkmcnt(4)
	v_add_f32_e32 v5, v74, v6
	s_waitcnt lgkmcnt(3)
	v_add_f32_e32 v6, v54, v7
	s_waitcnt lgkmcnt(2)
	v_add_f32_e32 v7, v38, v9
	s_waitcnt lgkmcnt(1)
	v_add_f32_e32 v9, v22, v11
	s_waitcnt lgkmcnt(0)
	v_add_f32_e32 v11, v8, v12
	v_bitop3_b32 v17, v10, s18, v196 bitop3:0x6c
	ds_bpermute_b32 v8, v17, v2
	ds_bpermute_b32 v10, v17, v3
	ds_bpermute_b32 v12, v17, v4
	ds_bpermute_b32 v13, v17, v5
	ds_bpermute_b32 v14, v17, v6
	ds_bpermute_b32 v15, v17, v7
	ds_bpermute_b32 v16, v17, v9
	ds_bpermute_b32 v17, v17, v11
	s_and_saveexec_b64 s[18:19], s[2:3]
	s_cbranch_execz .LBB0_855
	s_waitcnt lgkmcnt(5)
	v_add_f32_e32 v12, v4, v12
	v_add_f32_e32 v4, v2, v8
	s_mov_b32 s20, 0x49800000
	v_fma_f32 v4, v4, s20, 0.5
	v_trunc_f32_e32 v4, v4
	s_waitcnt lgkmcnt(4)
	v_add_f32_e32 v13, v5, v13
	v_mul_f32_e32 v5, 0x2f800000, v4
	v_floor_f32_e32 v5, v5
	v_fmac_f32_e32 v4, 0xcf800000, v5
	v_cvt_u32_f32_e32 v4, v4
	v_cvt_u32_f32_e32 v5, v5
	v_add_f32_e32 v10, v3, v10
	v_lshl_add_u64 v[2:3], v[214:215], 3, s[80:81]
	s_waitcnt lgkmcnt(3)
	v_add_f32_e32 v6, v6, v14
	global_atomic_add_x2 v[2:3], v[4:5], off
	v_fma_f32 v4, v10, s20, 0.5
	v_trunc_f32_e32 v4, v4
	v_mul_f32_e32 v5, 0x2f800000, v4
	v_floor_f32_e32 v5, v5
	v_fmac_f32_e32 v4, 0xcf800000, v5
	v_cvt_u32_f32_e32 v4, v4
	v_cvt_u32_f32_e32 v5, v5
	s_waitcnt lgkmcnt(2)
	v_add_f32_e32 v7, v7, v15
	s_waitcnt lgkmcnt(1)
	v_add_f32_e32 v9, v9, v16
	s_waitcnt lgkmcnt(0)
	v_add_f32_e32 v11, v11, v17
	global_atomic_add_x2 v[2:3], v[4:5], off offset:128
	v_fma_f32 v4, v12, s20, 0.5
	v_trunc_f32_e32 v4, v4
	v_mul_f32_e32 v5, 0x2f800000, v4
	v_floor_f32_e32 v5, v5
	v_fmac_f32_e32 v4, 0xcf800000, v5
	v_cvt_u32_f32_e32 v4, v4
	v_cvt_u32_f32_e32 v5, v5
	global_atomic_add_x2 v[2:3], v[4:5], off offset:256
	v_fma_f32 v4, v13, s20, 0.5
	v_trunc_f32_e32 v4, v4
	v_mul_f32_e32 v5, 0x2f800000, v4
	v_floor_f32_e32 v5, v5
	v_fmac_f32_e32 v4, 0xcf800000, v5
	v_cvt_u32_f32_e32 v4, v4
	v_cvt_u32_f32_e32 v5, v5
	global_atomic_add_x2 v[2:3], v[4:5], off offset:384
	v_fma_f32 v4, v6, s20, 0.5
	v_trunc_f32_e32 v4, v4
	v_mul_f32_e32 v5, 0x2f800000, v4
	v_floor_f32_e32 v5, v5
	v_fmac_f32_e32 v4, 0xcf800000, v5
	v_cvt_u32_f32_e32 v4, v4
	v_cvt_u32_f32_e32 v5, v5
	global_atomic_add_x2 v[2:3], v[4:5], off offset:1024
	v_fma_f32 v4, v7, s20, 0.5
	v_trunc_f32_e32 v4, v4
	v_mul_f32_e32 v5, 0x2f800000, v4
	v_floor_f32_e32 v5, v5
	v_fmac_f32_e32 v4, 0xcf800000, v5
	v_cvt_u32_f32_e32 v4, v4
	v_cvt_u32_f32_e32 v5, v5
	global_atomic_add_x2 v[2:3], v[4:5], off offset:1152
	v_fma_f32 v4, v9, s20, 0.5
	v_trunc_f32_e32 v4, v4
	v_mul_f32_e32 v5, 0x2f800000, v4
	v_floor_f32_e32 v5, v5
	v_fmac_f32_e32 v4, 0xcf800000, v5
	v_cvt_u32_f32_e32 v4, v4
	v_cvt_u32_f32_e32 v5, v5
	global_atomic_add_x2 v[2:3], v[4:5], off offset:1280
	v_fma_f32 v4, v11, s20, 0.5
	v_trunc_f32_e32 v4, v4
	v_mul_f32_e32 v5, 0x2f800000, v4
	v_floor_f32_e32 v5, v5
	v_fmac_f32_e32 v4, 0xcf800000, v5
	v_cvt_u32_f32_e32 v4, v4
	v_cvt_u32_f32_e32 v5, v5
	global_atomic_add_x2 v[2:3], v[4:5], off offset:1408

.Lalign_l8:
	s_movk_i32 s18, 0x80
	s_waitcnt vmcnt(15)
	v_lshlrev_b32_e32 v200, 16, v190
	v_and_b32_e32 v201, 0xffff0000, v190
	v_lshlrev_b32_e32 v190, 16, v191
	v_and_b32_e32 v191, 0xffff0000, v191
	v_pk_add_f32 v[186:187], v[186:187], v[200:201]
	v_pk_add_f32 v[188:189], v[188:189], v[190:191]
	v_cvt_pk_bf16_f32 v186, v186, v187
	v_cvt_pk_bf16_f32 v187, v188, v189
	v_lshlrev_b32_e32 v188, 16, v192
	v_and_b32_e32 v189, 0xffff0000, v192
	v_pk_add_f32 v[182:183], v[182:183], v[188:189]
	s_nop 0
	v_cvt_pk_bf16_f32 v188, v182, v183
	v_lshlrev_b32_e32 v182, 16, v193
	v_and_b32_e32 v183, 0xffff0000, v193
	v_pk_add_f32 v[182:183], v[184:185], v[182:183]
	v_and_b32_e32 v185, 0xffff0000, v187
	v_cvt_pk_bf16_f32 v189, v182, v183
	v_and_b32_e32 v183, 0xffff0000, v186
	v_lshlrev_b32_e32 v182, 16, v186
	v_mul_f32_e32 v183, v183, v183
	v_lshlrev_b32_e32 v184, 16, v187
	v_fmac_f32_e32 v183, v182, v182
	v_mul_f32_e32 v182, v185, v185
	global_store_dwordx4 v[232:233], v[186:189], off
	v_fmac_f32_e32 v182, v184, v184
	v_add_f32_e32 v182, v183, v182
	v_lshlrev_b32_e32 v186, 16, v188
	v_and_b32_e32 v187, 0xffff0000, v188
	v_lshlrev_b32_e32 v188, 16, v189
	v_and_b32_e32 v189, 0xffff0000, v189
	v_mul_f32_e32 v183, v187, v187
	v_mul_f32_e32 v184, v189, v189
	v_fmac_f32_e32 v183, v186, v186
	v_fmac_f32_e32 v184, v188, v188
	v_add_f32_e32 v183, v183, v184
	v_add_f32_e32 v184, v182, v183
	s_waitcnt vmcnt(15)
	v_lshlrev_b32_e32 v182, 16, v178
	v_and_b32_e32 v183, 0xffff0000, v178
	v_lshlrev_b32_e32 v178, 16, v179
	v_and_b32_e32 v179, 0xffff0000, v179
	v_pk_add_f32 v[166:167], v[166:167], v[182:183]
	v_pk_add_f32 v[168:169], v[168:169], v[178:179]
	v_cvt_pk_bf16_f32 v166, v166, v167
	v_cvt_pk_bf16_f32 v167, v168, v169
	v_lshlrev_b32_e32 v168, 16, v180
	v_and_b32_e32 v169, 0xffff0000, v180
	v_pk_add_f32 v[146:147], v[146:147], v[168:169]
	s_nop 0
	v_cvt_pk_bf16_f32 v168, v146, v147
	v_lshlrev_b32_e32 v146, 16, v181
	v_and_b32_e32 v147, 0xffff0000, v181
	v_pk_add_f32 v[146:147], v[148:149], v[146:147]
	v_and_b32_e32 v149, 0xffff0000, v167
	v_cvt_pk_bf16_f32 v169, v146, v147
	v_and_b32_e32 v147, 0xffff0000, v166
	v_lshlrev_b32_e32 v146, 16, v166
	v_mul_f32_e32 v147, v147, v147
	v_lshlrev_b32_e32 v148, 16, v167
	v_fmac_f32_e32 v147, v146, v146
	v_mul_f32_e32 v146, v149, v149
	global_store_dwordx4 v[232:233], v[166:169], off offset:256
	v_fmac_f32_e32 v146, v148, v148
	v_add_f32_e32 v146, v147, v146
	v_and_b32_e32 v167, 0xffff0000, v168
	v_lshlrev_b32_e32 v166, 16, v168
	v_mul_f32_e32 v147, v167, v167
	v_fmac_f32_e32 v147, v166, v166
	s_waitcnt vmcnt(15)
	v_lshlrev_b32_e32 v166, 16, v174
	v_and_b32_e32 v167, 0xffff0000, v174
	v_pk_add_f32 v[138:139], v[138:139], v[166:167]
	v_lshlrev_b32_e32 v166, 16, v175
	v_and_b32_e32 v167, 0xffff0000, v175
	v_pk_add_f32 v[140:141], v[140:141], v[166:167]
	v_cvt_pk_bf16_f32 v138, v138, v139
	v_cvt_pk_bf16_f32 v139, v140, v141
	v_lshlrev_b32_e32 v140, 16, v176
	v_and_b32_e32 v141, 0xffff0000, v176
	v_pk_add_f32 v[134:135], v[134:135], v[140:141]
	v_lshlrev_b32_e32 v168, 16, v169
	v_and_b32_e32 v169, 0xffff0000, v169
	v_cvt_pk_bf16_f32 v140, v134, v135
	v_lshlrev_b32_e32 v134, 16, v177
	v_and_b32_e32 v135, 0xffff0000, v177
	v_mul_f32_e32 v148, v169, v169
	v_pk_add_f32 v[134:135], v[136:137], v[134:135]
	v_fmac_f32_e32 v148, v168, v168
	v_cvt_pk_bf16_f32 v141, v134, v135
	v_and_b32_e32 v135, 0xffff0000, v138
	v_add_f32_e32 v147, v147, v148
	v_lshl_add_u64 v[148:149], s[86:87], 0, v[230:231]
	v_lshlrev_b32_e32 v134, 16, v138
	v_and_b32_e32 v137, 0xffff0000, v139
	v_mul_f32_e32 v135, v135, v135
	v_lshl_add_u64 v[148:149], v[148:149], 0, v[216:217]
	v_lshlrev_b32_e32 v136, 16, v139
	v_fmac_f32_e32 v135, v134, v134
	v_mul_f32_e32 v134, v137, v137
	global_store_dwordx4 v[148:149], v[138:141], off
	v_fmac_f32_e32 v134, v136, v136
	v_add_f32_e32 v134, v135, v134
	v_lshlrev_b32_e32 v138, 16, v140
	v_and_b32_e32 v139, 0xffff0000, v140
	v_lshlrev_b32_e32 v140, 16, v141
	v_and_b32_e32 v141, 0xffff0000, v141
	v_mul_f32_e32 v135, v139, v139
	v_mul_f32_e32 v136, v141, v141
	v_fmac_f32_e32 v135, v138, v138
	v_fmac_f32_e32 v136, v140, v140
	v_add_f32_e32 v135, v135, v136
	v_add_f32_e32 v136, v134, v135
	s_waitcnt vmcnt(15)
	v_lshlrev_b32_e32 v134, 16, v170
	v_and_b32_e32 v135, 0xffff0000, v170
	v_pk_add_f32 v[126:127], v[126:127], v[134:135]
	v_lshlrev_b32_e32 v134, 16, v171
	v_and_b32_e32 v135, 0xffff0000, v171
	v_pk_add_f32 v[128:129], v[128:129], v[134:135]
	v_cvt_pk_bf16_f32 v126, v126, v127
	v_cvt_pk_bf16_f32 v127, v128, v129
	v_lshlrev_b32_e32 v128, 16, v172
	v_and_b32_e32 v129, 0xffff0000, v172
	v_pk_add_f32 v[122:123], v[122:123], v[128:129]
	v_add_f32_e32 v146, v146, v147
	v_cvt_pk_bf16_f32 v128, v122, v123
	v_lshlrev_b32_e32 v122, 16, v173
	v_and_b32_e32 v123, 0xffff0000, v173
	v_pk_add_f32 v[122:123], v[124:125], v[122:123]
	v_and_b32_e32 v125, 0xffff0000, v127
	v_cvt_pk_bf16_f32 v129, v122, v123
	v_and_b32_e32 v123, 0xffff0000, v126
	v_lshlrev_b32_e32 v122, 16, v126
	v_mul_f32_e32 v123, v123, v123
	v_lshlrev_b32_e32 v124, 16, v127
	v_fmac_f32_e32 v123, v122, v122
	v_mul_f32_e32 v122, v125, v125
	global_store_dwordx4 v[148:149], v[126:129], off offset:256
	v_fmac_f32_e32 v122, v124, v124
	v_add_f32_e32 v122, v123, v122
	v_and_b32_e32 v127, 0xffff0000, v128
	v_lshlrev_b32_e32 v126, 16, v128
	v_mul_f32_e32 v123, v127, v127
	v_fmac_f32_e32 v123, v126, v126
	s_waitcnt vmcnt(15)
	v_lshlrev_b32_e32 v126, 16, v162
	v_and_b32_e32 v127, 0xffff0000, v162
	v_pk_add_f32 v[114:115], v[114:115], v[126:127]
	v_lshlrev_b32_e32 v126, 16, v163
	v_and_b32_e32 v127, 0xffff0000, v163
	v_pk_add_f32 v[116:117], v[116:117], v[126:127]
	v_cvt_pk_bf16_f32 v114, v114, v115
	v_cvt_pk_bf16_f32 v115, v116, v117
	v_lshlrev_b32_e32 v116, 16, v164
	v_and_b32_e32 v117, 0xffff0000, v164
	v_pk_add_f32 v[110:111], v[110:111], v[116:117]
	v_lshlrev_b32_e32 v128, 16, v129
	v_and_b32_e32 v129, 0xffff0000, v129
	v_cvt_pk_bf16_f32 v116, v110, v111
	v_lshlrev_b32_e32 v110, 16, v165
	v_and_b32_e32 v111, 0xffff0000, v165
	v_mul_f32_e32 v124, v129, v129
	v_pk_add_f32 v[110:111], v[112:113], v[110:111]
	v_fmac_f32_e32 v124, v128, v128
	v_cvt_pk_bf16_f32 v117, v110, v111
	v_and_b32_e32 v111, 0xffff0000, v114
	v_add_f32_e32 v123, v123, v124
	v_lshl_add_u64 v[124:125], s[86:87], 0, v[228:229]
	v_lshlrev_b32_e32 v110, 16, v114
	v_and_b32_e32 v113, 0xffff0000, v115
	v_mul_f32_e32 v111, v111, v111
	v_lshl_add_u64 v[124:125], v[124:125], 0, v[216:217]
	v_lshlrev_b32_e32 v112, 16, v115
	v_fmac_f32_e32 v111, v110, v110
	v_mul_f32_e32 v110, v113, v113
	global_store_dwordx4 v[124:125], v[114:117], off
	v_fmac_f32_e32 v110, v112, v112
	v_add_f32_e32 v110, v111, v110
	v_lshlrev_b32_e32 v114, 16, v116
	v_and_b32_e32 v115, 0xffff0000, v116
	v_lshlrev_b32_e32 v116, 16, v117
	v_and_b32_e32 v117, 0xffff0000, v117
	v_mul_f32_e32 v111, v115, v115
	v_mul_f32_e32 v112, v117, v117
	v_fmac_f32_e32 v111, v114, v114
	v_fmac_f32_e32 v112, v116, v116
	v_add_f32_e32 v111, v111, v112
	v_add_f32_e32 v112, v110, v111
	s_waitcnt vmcnt(15)
	v_lshlrev_b32_e32 v110, 16, v158
	v_and_b32_e32 v111, 0xffff0000, v158
	v_pk_add_f32 v[102:103], v[102:103], v[110:111]
	v_lshlrev_b32_e32 v110, 16, v159
	v_and_b32_e32 v111, 0xffff0000, v159
	v_pk_add_f32 v[104:105], v[104:105], v[110:111]
	v_cvt_pk_bf16_f32 v102, v102, v103
	v_cvt_pk_bf16_f32 v103, v104, v105
	v_lshlrev_b32_e32 v104, 16, v160
	v_and_b32_e32 v105, 0xffff0000, v160
	v_pk_add_f32 v[94:95], v[94:95], v[104:105]
	v_add_f32_e32 v122, v122, v123
	v_cvt_pk_bf16_f32 v104, v94, v95
	v_lshlrev_b32_e32 v94, 16, v161
	v_and_b32_e32 v95, 0xffff0000, v161
	v_pk_add_f32 v[94:95], v[96:97], v[94:95]
	v_and_b32_e32 v97, 0xffff0000, v103
	v_cvt_pk_bf16_f32 v105, v94, v95
	v_and_b32_e32 v95, 0xffff0000, v102
	v_lshlrev_b32_e32 v94, 16, v102
	v_mul_f32_e32 v95, v95, v95
	v_lshlrev_b32_e32 v96, 16, v103
	v_fmac_f32_e32 v95, v94, v94
	v_mul_f32_e32 v94, v97, v97
	global_store_dwordx4 v[124:125], v[102:105], off offset:256
	v_fmac_f32_e32 v94, v96, v96
	v_add_f32_e32 v94, v95, v94
	v_and_b32_e32 v103, 0xffff0000, v104
	v_lshlrev_b32_e32 v102, 16, v104
	v_mul_f32_e32 v95, v103, v103
	v_fmac_f32_e32 v95, v102, v102
	s_waitcnt vmcnt(15)
	v_lshlrev_b32_e32 v102, 16, v154
	v_and_b32_e32 v103, 0xffff0000, v154
	v_pk_add_f32 v[90:91], v[90:91], v[102:103]
	v_lshlrev_b32_e32 v102, 16, v155
	v_and_b32_e32 v103, 0xffff0000, v155
	v_pk_add_f32 v[92:93], v[92:93], v[102:103]
	v_cvt_pk_bf16_f32 v90, v90, v91
	v_cvt_pk_bf16_f32 v91, v92, v93
	v_lshlrev_b32_e32 v92, 16, v156
	v_and_b32_e32 v93, 0xffff0000, v156
	v_pk_add_f32 v[82:83], v[82:83], v[92:93]
	v_lshlrev_b32_e32 v104, 16, v105
	v_and_b32_e32 v105, 0xffff0000, v105
	v_cvt_pk_bf16_f32 v92, v82, v83
	v_lshlrev_b32_e32 v82, 16, v157
	v_and_b32_e32 v83, 0xffff0000, v157
	v_mul_f32_e32 v96, v105, v105
	v_pk_add_f32 v[82:83], v[84:85], v[82:83]
	v_fmac_f32_e32 v96, v104, v104
	v_cvt_pk_bf16_f32 v93, v82, v83
	v_and_b32_e32 v83, 0xffff0000, v90
	v_add_f32_e32 v95, v95, v96
	v_lshl_add_u64 v[96:97], s[86:87], 0, v[226:227]
	v_lshlrev_b32_e32 v82, 16, v90
	v_and_b32_e32 v85, 0xffff0000, v91
	v_mul_f32_e32 v83, v83, v83
	v_lshl_add_u64 v[96:97], v[96:97], 0, v[216:217]
	v_lshlrev_b32_e32 v84, 16, v91
	v_fmac_f32_e32 v83, v82, v82
	v_mul_f32_e32 v82, v85, v85
	global_store_dwordx4 v[96:97], v[90:93], off
	v_fmac_f32_e32 v82, v84, v84
	v_add_f32_e32 v82, v83, v82
	v_lshlrev_b32_e32 v90, 16, v92
	v_and_b32_e32 v91, 0xffff0000, v92
	v_lshlrev_b32_e32 v92, 16, v93
	v_and_b32_e32 v93, 0xffff0000, v93
	v_mul_f32_e32 v83, v91, v91
	v_mul_f32_e32 v84, v93, v93
	v_fmac_f32_e32 v83, v90, v90
	v_fmac_f32_e32 v84, v92, v92
	v_add_f32_e32 v83, v83, v84
	v_add_f32_e32 v84, v82, v83
	s_waitcnt vmcnt(15)
	v_lshlrev_b32_e32 v82, 16, v150
	v_and_b32_e32 v83, 0xffff0000, v150
	v_pk_add_f32 v[74:75], v[74:75], v[82:83]
	v_lshlrev_b32_e32 v82, 16, v151
	v_and_b32_e32 v83, 0xffff0000, v151
	v_pk_add_f32 v[76:77], v[76:77], v[82:83]
	v_cvt_pk_bf16_f32 v74, v74, v75
	v_cvt_pk_bf16_f32 v75, v76, v77
	v_lshlrev_b32_e32 v76, 16, v152
	v_and_b32_e32 v77, 0xffff0000, v152
	v_pk_add_f32 v[70:71], v[70:71], v[76:77]
	v_add_f32_e32 v94, v94, v95
	v_cvt_pk_bf16_f32 v76, v70, v71
	v_lshlrev_b32_e32 v70, 16, v153
	v_and_b32_e32 v71, 0xffff0000, v153
	v_pk_add_f32 v[70:71], v[72:73], v[70:71]
	v_and_b32_e32 v73, 0xffff0000, v75
	v_cvt_pk_bf16_f32 v77, v70, v71
	v_and_b32_e32 v71, 0xffff0000, v74
	v_lshlrev_b32_e32 v70, 16, v74
	v_mul_f32_e32 v71, v71, v71
	v_lshlrev_b32_e32 v72, 16, v75
	v_fmac_f32_e32 v71, v70, v70
	v_mul_f32_e32 v70, v73, v73
	global_store_dwordx4 v[96:97], v[74:77], off offset:256
	v_fmac_f32_e32 v70, v72, v72
	v_add_f32_e32 v70, v71, v70
	v_lshlrev_b32_e32 v74, 16, v76
	v_and_b32_e32 v75, 0xffff0000, v76
	v_lshlrev_b32_e32 v76, 16, v77
	v_and_b32_e32 v77, 0xffff0000, v77
	v_mul_f32_e32 v71, v75, v75
	v_mul_f32_e32 v72, v77, v77
	v_fmac_f32_e32 v71, v74, v74
	v_fmac_f32_e32 v72, v76, v76
	v_add_f32_e32 v71, v71, v72
	s_waitcnt vmcnt(15)
	v_lshlrev_b32_e32 v72, 16, v142
	v_and_b32_e32 v73, 0xffff0000, v142
	v_pk_add_f32 v[62:63], v[62:63], v[72:73]
	v_lshlrev_b32_e32 v72, 16, v143
	v_and_b32_e32 v73, 0xffff0000, v143
	v_pk_add_f32 v[64:65], v[64:65], v[72:73]
	v_cvt_pk_bf16_f32 v62, v62, v63
	v_cvt_pk_bf16_f32 v63, v64, v65
	v_lshlrev_b32_e32 v64, 16, v144
	v_and_b32_e32 v65, 0xffff0000, v144
	v_pk_add_f32 v[58:59], v[58:59], v[64:65]
	v_add_f32_e32 v70, v70, v71
	v_cvt_pk_bf16_f32 v64, v58, v59
	v_lshlrev_b32_e32 v58, 16, v145
	v_and_b32_e32 v59, 0xffff0000, v145
	v_pk_add_f32 v[58:59], v[60:61], v[58:59]
	v_add_f32_e32 v74, v84, v70
	v_cvt_pk_bf16_f32 v65, v58, v59
	v_and_b32_e32 v59, 0xffff0000, v62
	v_lshl_add_u64 v[70:71], s[86:87], 0, v[224:225]
	v_lshlrev_b32_e32 v58, 16, v62
	v_and_b32_e32 v61, 0xffff0000, v63
	v_mul_f32_e32 v59, v59, v59
	v_lshl_add_u64 v[70:71], v[70:71], 0, v[216:217]
	v_lshlrev_b32_e32 v60, 16, v63
	v_fmac_f32_e32 v59, v58, v58
	v_mul_f32_e32 v58, v61, v61
	global_store_dwordx4 v[70:71], v[62:65], off
	v_fmac_f32_e32 v58, v60, v60
	v_add_f32_e32 v58, v59, v58
	v_lshlrev_b32_e32 v62, 16, v64
	v_and_b32_e32 v63, 0xffff0000, v64
	v_lshlrev_b32_e32 v64, 16, v65
	v_and_b32_e32 v65, 0xffff0000, v65
	v_mul_f32_e32 v59, v63, v63
	v_mul_f32_e32 v60, v65, v65
	v_fmac_f32_e32 v59, v62, v62
	v_fmac_f32_e32 v60, v64, v64
	v_add_f32_e32 v59, v59, v60
	v_add_f32_e32 v60, v58, v59
	s_waitcnt vmcnt(15)
	v_lshlrev_b32_e32 v58, 16, v130
	v_and_b32_e32 v59, 0xffff0000, v130
	v_pk_add_f32 v[54:55], v[54:55], v[58:59]
	v_lshlrev_b32_e32 v58, 16, v131
	v_and_b32_e32 v59, 0xffff0000, v131
	v_pk_add_f32 v[56:57], v[56:57], v[58:59]
	v_cvt_pk_bf16_f32 v54, v54, v55
	v_cvt_pk_bf16_f32 v55, v56, v57
	v_lshlrev_b32_e32 v56, 16, v132
	v_and_b32_e32 v57, 0xffff0000, v132
	v_pk_add_f32 v[50:51], v[50:51], v[56:57]
	v_add_f32_e32 v146, v184, v146
	v_cvt_pk_bf16_f32 v56, v50, v51
	v_lshlrev_b32_e32 v50, 16, v133
	v_and_b32_e32 v51, 0xffff0000, v133
	v_pk_add_f32 v[50:51], v[52:53], v[50:51]
	v_and_b32_e32 v53, 0xffff0000, v55
	v_cvt_pk_bf16_f32 v57, v50, v51
	v_and_b32_e32 v51, 0xffff0000, v54
	v_lshlrev_b32_e32 v50, 16, v54
	v_mul_f32_e32 v51, v51, v51
	v_lshlrev_b32_e32 v52, 16, v55
	v_fmac_f32_e32 v51, v50, v50
	v_mul_f32_e32 v50, v53, v53
	global_store_dwordx4 v[70:71], v[54:57], off offset:256
	v_fmac_f32_e32 v50, v52, v52
	v_add_f32_e32 v50, v51, v50
	v_lshlrev_b32_e32 v54, 16, v56
	v_and_b32_e32 v55, 0xffff0000, v56
	v_lshlrev_b32_e32 v56, 16, v57
	v_and_b32_e32 v57, 0xffff0000, v57
	v_mul_f32_e32 v51, v55, v55
	v_mul_f32_e32 v52, v57, v57
	v_fmac_f32_e32 v51, v54, v54
	v_fmac_f32_e32 v52, v56, v56
	v_add_f32_e32 v51, v51, v52
	s_waitcnt vmcnt(15)
	v_lshlrev_b32_e32 v52, 16, v118
	v_and_b32_e32 v53, 0xffff0000, v118
	v_pk_add_f32 v[46:47], v[46:47], v[52:53]
	v_lshlrev_b32_e32 v52, 16, v119
	v_and_b32_e32 v53, 0xffff0000, v119
	v_pk_add_f32 v[48:49], v[48:49], v[52:53]
	v_cvt_pk_bf16_f32 v46, v46, v47
	v_cvt_pk_bf16_f32 v47, v48, v49
	v_lshlrev_b32_e32 v48, 16, v120
	v_and_b32_e32 v49, 0xffff0000, v120
	v_pk_add_f32 v[42:43], v[42:43], v[48:49]
	v_add_f32_e32 v50, v50, v51
	v_cvt_pk_bf16_f32 v48, v42, v43
	v_lshlrev_b32_e32 v42, 16, v121
	v_and_b32_e32 v43, 0xffff0000, v121
	v_pk_add_f32 v[42:43], v[44:45], v[42:43]
	v_add_f32_e32 v54, v60, v50
	v_cvt_pk_bf16_f32 v49, v42, v43
	v_and_b32_e32 v43, 0xffff0000, v46
	v_lshl_add_u64 v[50:51], s[86:87], 0, v[222:223]
	v_lshlrev_b32_e32 v42, 16, v46
	v_and_b32_e32 v45, 0xffff0000, v47
	v_mul_f32_e32 v43, v43, v43
	v_lshl_add_u64 v[50:51], v[50:51], 0, v[216:217]
	v_lshlrev_b32_e32 v44, 16, v47
	v_fmac_f32_e32 v43, v42, v42
	v_mul_f32_e32 v42, v45, v45
	global_store_dwordx4 v[50:51], v[46:49], off
	v_fmac_f32_e32 v42, v44, v44
	v_add_f32_e32 v42, v43, v42
	v_lshlrev_b32_e32 v46, 16, v48
	v_and_b32_e32 v47, 0xffff0000, v48
	v_lshlrev_b32_e32 v48, 16, v49
	v_and_b32_e32 v49, 0xffff0000, v49
	v_mul_f32_e32 v43, v47, v47
	v_mul_f32_e32 v44, v49, v49
	v_fmac_f32_e32 v43, v46, v46
	v_fmac_f32_e32 v44, v48, v48
	v_add_f32_e32 v43, v43, v44
	v_add_f32_e32 v44, v42, v43
	s_waitcnt vmcnt(15)
	v_lshlrev_b32_e32 v42, 16, v106
	v_and_b32_e32 v43, 0xffff0000, v106
	v_pk_add_f32 v[38:39], v[38:39], v[42:43]
	v_lshlrev_b32_e32 v42, 16, v107
	v_and_b32_e32 v43, 0xffff0000, v107
	v_pk_add_f32 v[40:41], v[40:41], v[42:43]
	v_cvt_pk_bf16_f32 v38, v38, v39
	v_cvt_pk_bf16_f32 v39, v40, v41
	v_lshlrev_b32_e32 v40, 16, v108
	v_and_b32_e32 v41, 0xffff0000, v108
	v_pk_add_f32 v[34:35], v[34:35], v[40:41]
	v_add_f32_e32 v122, v136, v122
	v_cvt_pk_bf16_f32 v40, v34, v35
	v_lshlrev_b32_e32 v34, 16, v109
	v_and_b32_e32 v35, 0xffff0000, v109
	v_pk_add_f32 v[34:35], v[36:37], v[34:35]
	v_and_b32_e32 v37, 0xffff0000, v39
	v_cvt_pk_bf16_f32 v41, v34, v35
	v_and_b32_e32 v35, 0xffff0000, v38
	v_lshlrev_b32_e32 v34, 16, v38
	v_mul_f32_e32 v35, v35, v35
	v_lshlrev_b32_e32 v36, 16, v39
	v_fmac_f32_e32 v35, v34, v34
	v_mul_f32_e32 v34, v37, v37
	global_store_dwordx4 v[50:51], v[38:41], off offset:256
	v_fmac_f32_e32 v34, v36, v36
	v_add_f32_e32 v34, v35, v34
	v_lshlrev_b32_e32 v38, 16, v40
	v_and_b32_e32 v39, 0xffff0000, v40
	v_lshlrev_b32_e32 v40, 16, v41
	v_and_b32_e32 v41, 0xffff0000, v41
	v_mul_f32_e32 v35, v39, v39
	v_mul_f32_e32 v36, v41, v41
	v_fmac_f32_e32 v35, v38, v38
	v_fmac_f32_e32 v36, v40, v40
	v_add_f32_e32 v35, v35, v36
	s_waitcnt vmcnt(15)
	v_lshlrev_b32_e32 v36, 16, v98
	v_and_b32_e32 v37, 0xffff0000, v98
	v_pk_add_f32 v[30:31], v[30:31], v[36:37]
	v_lshlrev_b32_e32 v36, 16, v99
	v_and_b32_e32 v37, 0xffff0000, v99
	v_pk_add_f32 v[32:33], v[32:33], v[36:37]
	v_cvt_pk_bf16_f32 v30, v30, v31
	v_cvt_pk_bf16_f32 v31, v32, v33
	v_lshlrev_b32_e32 v32, 16, v100
	v_and_b32_e32 v33, 0xffff0000, v100
	v_pk_add_f32 v[26:27], v[26:27], v[32:33]
	v_add_f32_e32 v34, v34, v35
	v_cvt_pk_bf16_f32 v32, v26, v27
	v_lshlrev_b32_e32 v26, 16, v101
	v_and_b32_e32 v27, 0xffff0000, v101
	v_pk_add_f32 v[26:27], v[28:29], v[26:27]
	v_add_f32_e32 v38, v44, v34
	v_cvt_pk_bf16_f32 v33, v26, v27
	v_and_b32_e32 v27, 0xffff0000, v30
	v_lshl_add_u64 v[34:35], s[86:87], 0, v[220:221]
	v_lshlrev_b32_e32 v26, 16, v30
	v_and_b32_e32 v29, 0xffff0000, v31
	v_mul_f32_e32 v27, v27, v27
	v_lshl_add_u64 v[34:35], v[34:35], 0, v[216:217]
	v_lshlrev_b32_e32 v28, 16, v31
	v_fmac_f32_e32 v27, v26, v26
	v_mul_f32_e32 v26, v29, v29
	global_store_dwordx4 v[34:35], v[30:33], off
	v_fmac_f32_e32 v26, v28, v28
	v_add_f32_e32 v26, v27, v26
	v_lshlrev_b32_e32 v30, 16, v32
	v_and_b32_e32 v31, 0xffff0000, v32
	v_lshlrev_b32_e32 v32, 16, v33
	v_and_b32_e32 v33, 0xffff0000, v33
	v_mul_f32_e32 v27, v31, v31
	v_mul_f32_e32 v28, v33, v33
	v_fmac_f32_e32 v27, v30, v30
	v_fmac_f32_e32 v28, v32, v32
	v_add_f32_e32 v27, v27, v28
	v_add_f32_e32 v28, v26, v27
	s_waitcnt vmcnt(15)
	v_lshlrev_b32_e32 v26, 16, v86
	v_and_b32_e32 v27, 0xffff0000, v86
	v_pk_add_f32 v[22:23], v[22:23], v[26:27]
	v_lshlrev_b32_e32 v26, 16, v87
	v_and_b32_e32 v27, 0xffff0000, v87
	v_pk_add_f32 v[24:25], v[24:25], v[26:27]
	v_cvt_pk_bf16_f32 v22, v22, v23
	v_cvt_pk_bf16_f32 v23, v24, v25
	v_lshlrev_b32_e32 v24, 16, v88
	v_and_b32_e32 v25, 0xffff0000, v88
	v_pk_add_f32 v[18:19], v[18:19], v[24:25]
	v_add_f32_e32 v94, v112, v94
	v_cvt_pk_bf16_f32 v24, v18, v19
	v_lshlrev_b32_e32 v18, 16, v89
	v_and_b32_e32 v19, 0xffff0000, v89
	v_pk_add_f32 v[18:19], v[20:21], v[18:19]
	v_and_b32_e32 v21, 0xffff0000, v23
	v_cvt_pk_bf16_f32 v25, v18, v19
	v_and_b32_e32 v19, 0xffff0000, v22
	v_lshlrev_b32_e32 v18, 16, v22
	v_mul_f32_e32 v19, v19, v19
	v_lshlrev_b32_e32 v20, 16, v23
	v_fmac_f32_e32 v19, v18, v18
	v_mul_f32_e32 v18, v21, v21
	global_store_dwordx4 v[34:35], v[22:25], off offset:256
	v_fmac_f32_e32 v18, v20, v20
	v_add_f32_e32 v18, v19, v18
	v_lshlrev_b32_e32 v22, 16, v24
	v_and_b32_e32 v23, 0xffff0000, v24
	v_lshlrev_b32_e32 v24, 16, v25
	v_and_b32_e32 v25, 0xffff0000, v25
	v_mul_f32_e32 v19, v23, v23
	v_mul_f32_e32 v20, v25, v25
	v_fmac_f32_e32 v19, v22, v22
	v_fmac_f32_e32 v20, v24, v24
	v_add_f32_e32 v19, v19, v20
	s_waitcnt vmcnt(15)
	v_lshlrev_b32_e32 v20, 16, v78
	v_and_b32_e32 v21, 0xffff0000, v78
	v_pk_add_f32 v[14:15], v[14:15], v[20:21]
	v_lshlrev_b32_e32 v20, 16, v79
	v_and_b32_e32 v21, 0xffff0000, v79
	v_pk_add_f32 v[16:17], v[16:17], v[20:21]
	v_cvt_pk_bf16_f32 v14, v14, v15
	v_cvt_pk_bf16_f32 v15, v16, v17
	v_lshlrev_b32_e32 v16, 16, v80
	v_and_b32_e32 v17, 0xffff0000, v80
	v_pk_add_f32 v[10:11], v[10:11], v[16:17]
	v_add_f32_e32 v18, v18, v19
	v_cvt_pk_bf16_f32 v16, v10, v11
	v_lshlrev_b32_e32 v10, 16, v81
	v_and_b32_e32 v11, 0xffff0000, v81
	v_pk_add_f32 v[10:11], v[12:13], v[10:11]
	v_add_f32_e32 v22, v28, v18
	v_cvt_pk_bf16_f32 v17, v10, v11
	v_and_b32_e32 v11, 0xffff0000, v14
	v_lshl_add_u64 v[18:19], s[86:87], 0, v[218:219]
	v_lshlrev_b32_e32 v10, 16, v14
	v_and_b32_e32 v13, 0xffff0000, v15
	v_mul_f32_e32 v11, v11, v11
	v_lshl_add_u64 v[18:19], v[18:19], 0, v[216:217]
	v_lshlrev_b32_e32 v12, 16, v15
	v_fmac_f32_e32 v11, v10, v10
	v_mul_f32_e32 v10, v13, v13
	global_store_dwordx4 v[18:19], v[14:17], off
	v_fmac_f32_e32 v10, v12, v12
	v_add_f32_e32 v10, v11, v10
	v_lshlrev_b32_e32 v14, 16, v16
	v_and_b32_e32 v15, 0xffff0000, v16
	v_lshlrev_b32_e32 v16, 16, v17
	v_and_b32_e32 v17, 0xffff0000, v17
	v_mul_f32_e32 v11, v15, v15
	v_mul_f32_e32 v12, v17, v17
	v_fmac_f32_e32 v11, v14, v14
	v_fmac_f32_e32 v12, v16, v16
	v_add_f32_e32 v11, v11, v12
	v_add_f32_e32 v12, v10, v11
	s_waitcnt vmcnt(15)
	v_lshlrev_b32_e32 v10, 16, v66
	v_and_b32_e32 v11, 0xffff0000, v66
	v_pk_add_f32 v[6:7], v[6:7], v[10:11]
	v_lshlrev_b32_e32 v10, 16, v67
	v_and_b32_e32 v11, 0xffff0000, v67
	v_pk_add_f32 v[8:9], v[8:9], v[10:11]
	v_cvt_pk_bf16_f32 v6, v6, v7
	v_cvt_pk_bf16_f32 v7, v8, v9
	v_lshlrev_b32_e32 v8, 16, v68
	v_and_b32_e32 v9, 0xffff0000, v68
	v_pk_add_f32 v[2:3], v[2:3], v[8:9]
	s_nop 0
	v_cvt_pk_bf16_f32 v8, v2, v3
	v_lshlrev_b32_e32 v2, 16, v69
	v_and_b32_e32 v3, 0xffff0000, v69
	v_pk_add_f32 v[2:3], v[4:5], v[2:3]
	v_and_b32_e32 v5, 0xffff0000, v7
	v_cvt_pk_bf16_f32 v9, v2, v3
	v_and_b32_e32 v3, 0xffff0000, v6
	v_lshlrev_b32_e32 v2, 16, v6
	v_mul_f32_e32 v3, v3, v3
	v_lshlrev_b32_e32 v4, 16, v7
	v_fmac_f32_e32 v3, v2, v2
	v_mul_f32_e32 v2, v5, v5
	global_store_dwordx4 v[18:19], v[6:9], off offset:256
	v_fmac_f32_e32 v2, v4, v4
	v_add_f32_e32 v2, v3, v2
	v_lshlrev_b32_e32 v6, 16, v8
	v_and_b32_e32 v7, 0xffff0000, v8
	v_lshlrev_b32_e32 v8, 16, v9
	v_and_b32_e32 v9, 0xffff0000, v9
	v_mul_f32_e32 v3, v7, v7
	v_mul_f32_e32 v4, v9, v9
	v_fmac_f32_e32 v3, v6, v6
	v_fmac_f32_e32 v4, v8, v8
	v_add_f32_e32 v3, v3, v4
	v_add_f32_e32 v2, v2, v3
	v_add_f32_e32 v8, v12, v2
	v_mov_b32_e32 v2, v0
	s_nop 0
	v_lshlrev_b32_e32 v10, 2, v2
	v_bitop3_b32 v2, v10, 64, v196 bitop3:0x6c
	ds_bpermute_b32 v3, v2, v146
	ds_bpermute_b32 v4, v2, v122
	ds_bpermute_b32 v5, v2, v94
	ds_bpermute_b32 v6, v2, v74
	ds_bpermute_b32 v7, v2, v54
	ds_bpermute_b32 v9, v2, v38
	ds_bpermute_b32 v11, v2, v22
	ds_bpermute_b32 v12, v2, v8
	s_waitcnt lgkmcnt(7)
	v_add_f32_e32 v2, v146, v3
	s_waitcnt lgkmcnt(6)
	v_add_f32_e32 v3, v122, v4
	s_waitcnt lgkmcnt(5)
	v_add_f32_e32 v4, v94, v5
	s_waitcnt lgkmcnt(4)
	v_add_f32_e32 v5, v74, v6
	s_waitcnt lgkmcnt(3)
	v_add_f32_e32 v6, v54, v7
	s_waitcnt lgkmcnt(2)
	v_add_f32_e32 v7, v38, v9
	s_waitcnt lgkmcnt(1)
	v_add_f32_e32 v9, v22, v11
	s_waitcnt lgkmcnt(0)
	v_add_f32_e32 v11, v8, v12
	v_bitop3_b32 v17, v10, s18, v196 bitop3:0x6c
	ds_bpermute_b32 v8, v17, v2
	ds_bpermute_b32 v10, v17, v3
	ds_bpermute_b32 v12, v17, v4
	ds_bpermute_b32 v13, v17, v5
	ds_bpermute_b32 v14, v17, v6
	ds_bpermute_b32 v15, v17, v7
	ds_bpermute_b32 v16, v17, v9
	ds_bpermute_b32 v17, v17, v11
	s_and_saveexec_b64 s[18:19], s[2:3]
	s_cbranch_execz .LBB0_1446
	s_waitcnt lgkmcnt(5)
	v_add_f32_e32 v12, v4, v12
	v_add_f32_e32 v4, v2, v8
	s_mov_b32 s20, 0x49800000
	v_fma_f32 v4, v4, s20, 0.5
	v_trunc_f32_e32 v4, v4
	s_waitcnt lgkmcnt(4)
	v_add_f32_e32 v13, v5, v13
	v_mul_f32_e32 v5, 0x2f800000, v4
	v_floor_f32_e32 v5, v5
	v_fmac_f32_e32 v4, 0xcf800000, v5
	v_cvt_u32_f32_e32 v4, v4
	v_cvt_u32_f32_e32 v5, v5
	v_add_f32_e32 v10, v3, v10
	v_lshl_add_u64 v[2:3], v[214:215], 3, s[10:11]
	s_waitcnt lgkmcnt(3)
	v_add_f32_e32 v6, v6, v14
	global_atomic_add_x2 v[2:3], v[4:5], off
	v_fma_f32 v4, v10, s20, 0.5
	v_trunc_f32_e32 v4, v4
	v_mul_f32_e32 v5, 0x2f800000, v4
	v_floor_f32_e32 v5, v5
	v_fmac_f32_e32 v4, 0xcf800000, v5
	v_cvt_u32_f32_e32 v4, v4
	v_cvt_u32_f32_e32 v5, v5
	s_waitcnt lgkmcnt(2)
	v_add_f32_e32 v7, v7, v15
	s_waitcnt lgkmcnt(1)
	v_add_f32_e32 v9, v9, v16
	s_waitcnt lgkmcnt(0)
	v_add_f32_e32 v11, v11, v17
	global_atomic_add_x2 v[2:3], v[4:5], off offset:128
	v_fma_f32 v4, v12, s20, 0.5
	v_trunc_f32_e32 v4, v4
	v_mul_f32_e32 v5, 0x2f800000, v4
	v_floor_f32_e32 v5, v5
	v_fmac_f32_e32 v4, 0xcf800000, v5
	v_cvt_u32_f32_e32 v4, v4
	v_cvt_u32_f32_e32 v5, v5
	global_atomic_add_x2 v[2:3], v[4:5], off offset:256
	v_fma_f32 v4, v13, s20, 0.5
	v_trunc_f32_e32 v4, v4
	v_mul_f32_e32 v5, 0x2f800000, v4
	v_floor_f32_e32 v5, v5
	v_fmac_f32_e32 v4, 0xcf800000, v5
	v_cvt_u32_f32_e32 v4, v4
	v_cvt_u32_f32_e32 v5, v5
	global_atomic_add_x2 v[2:3], v[4:5], off offset:384
	v_fma_f32 v4, v6, s20, 0.5
	v_trunc_f32_e32 v4, v4
	v_mul_f32_e32 v5, 0x2f800000, v4
	v_floor_f32_e32 v5, v5
	v_fmac_f32_e32 v4, 0xcf800000, v5
	v_cvt_u32_f32_e32 v4, v4
	v_cvt_u32_f32_e32 v5, v5
	global_atomic_add_x2 v[2:3], v[4:5], off offset:1024
	v_fma_f32 v4, v7, s20, 0.5
	v_trunc_f32_e32 v4, v4
	v_mul_f32_e32 v5, 0x2f800000, v4
	v_floor_f32_e32 v5, v5
	v_fmac_f32_e32 v4, 0xcf800000, v5
	v_cvt_u32_f32_e32 v4, v4
	v_cvt_u32_f32_e32 v5, v5
	global_atomic_add_x2 v[2:3], v[4:5], off offset:1152
	v_fma_f32 v4, v9, s20, 0.5
	v_trunc_f32_e32 v4, v4
	v_mul_f32_e32 v5, 0x2f800000, v4
	v_floor_f32_e32 v5, v5
	v_fmac_f32_e32 v4, 0xcf800000, v5
	v_cvt_u32_f32_e32 v4, v4
	v_cvt_u32_f32_e32 v5, v5
	global_atomic_add_x2 v[2:3], v[4:5], off offset:1280
	v_fma_f32 v4, v11, s20, 0.5
	v_trunc_f32_e32 v4, v4
	v_mul_f32_e32 v5, 0x2f800000, v4
	v_floor_f32_e32 v5, v5
	v_fmac_f32_e32 v4, 0xcf800000, v5
	v_cvt_u32_f32_e32 v4, v4
	v_cvt_u32_f32_e32 v5, v5
	global_atomic_add_x2 v[2:3], v[4:5], off offset:1408
